# all six GEMM K loops: per-phase s_setprio flips replaced by one static priority raise for waves 4-7 around the loop
# baseline (speedup 1.0000x reference)
; #define PG8_STAGE(bufoff, gbase, voff) do { _Pragma("unroll") for (int _i = 0; _i < 2; ++_i) \
;         __builtin_amdgcn_global_load_lds((const unsigned*)((const char*)(gbase) + (voff)[_i]), (LAS unsigned*)(lds + (bufoff) + ldsw + _i * 8192), 16, 0, 0); } while (0)
; #define PG8_LDA(dst, b, h) do { _Pragma("unroll") for (int m = 0; m < 4; ++m) _Pragma("unroll") for (int k = 0; k < 2; ++k) dst[m][k] = *(const LAS bf16x8*)(lds + PG8_SA(b, h) + aoff + m * 2048 + k * 1024); } while (0)
; #define PG8_LDB(dst, b, h) do { _Pragma("unroll") for (int n = 0; n < 2; ++n) _Pragma("unroll") for (int k = 0; k < 2; ++k) dst[n][k] = *(const LAS bf16x8*)(lds + PG8_SB(b, h) + boff + n * 2048 + k * 1024); } while (0)
; #define PG8_MMA(ai, bj, At, Bt) do { __builtin_amdgcn_s_setprio(1); _Pragma("unroll") for (int m = 0; m < 4; ++m) _Pragma("unroll") for (int n = 0; n < 2; ++n) _Pragma("unroll") for (int k = 0; k < 2; ++k) \
;         acc[ai][bj][m][n] = __builtin_amdgcn_mfma_f32_16x16x32_bf16(Bt[n][k], At[m][k], acc[ai][bj][m][n], 0, 0, 0); __builtin_amdgcn_s_setprio(0); } while (0)
; #define PG8_WAIT_V(n) asm volatile("s_waitcnt vmcnt(" #n ")" ::: "memory")
; #define PG8_WAIT_L(n) asm volatile("s_waitcnt lgkmcnt(" #n ")" ::: "memory")
; #define PG8_BAR __builtin_amdgcn_s_barrier()
; #define PG8_SCHED __builtin_amdgcn_sched_barrier(0)
; template <class Epi>
; __device__ __forceinline__ void gemm_phase(LAS unsigned char* lds, const Gemm g, const Epi& E) {
;     ...
;             PG8_LDB(B0, 0, 0); PG8_LDB(B1, 0, 1); PG8_SCHED; PG8_LDA(At, 0, 0); PG8_STAGE(PG8_SA(1, 1), a1 + hstepA, voffA);
;             PG8_WAIT_V(8); PG8_WAIT_L(0); PG8_BAR; PG8_MMA(0, 0, At, B0); PG8_MMA(0, 1, At, B1); PG8_BAR; PG8_SCHED;
;     ...
;         for (int a = 0; a < 2; ++a)
; #pragma unroll
;             for (int b = 0; b < 2; ++b)
; #pragma unroll
;                 for (int m = 0; m < 4; ++m)
; #pragma unroll
;                     for (int n = 0; n < 2; ++n) acc[a][b][m][n] = (f32x4){0.f, 0.f, 0.f, 0.f};
.Lin_ssq_skip:
	s_add_u32 s16, s16, 0x80
	s_addc_u32 s17, s17, 0
	s_add_u32 s20, s44, 0x100
	s_addc_u32 s21, s45, 0
	s_mov_b32 s35, 0
	v_mov_b64_e32 v[2:3], 0
	v_mov_b64_e32 v[4:5], 0
	v_mov_b64_e32 v[6:7], 0
	v_mov_b64_e32 v[8:9], 0
	v_mov_b64_e32 v[10:11], 0
	v_mov_b64_e32 v[12:13], 0
	v_mov_b64_e32 v[14:15], 0
	v_mov_b64_e32 v[16:17], 0
	v_mov_b64_e32 v[18:19], 0
	v_mov_b64_e32 v[20:21], 0
	v_mov_b64_e32 v[22:23], 0
	v_mov_b64_e32 v[24:25], 0
	v_mov_b64_e32 v[26:27], 0
	v_mov_b64_e32 v[28:29], 0
	v_mov_b64_e32 v[30:31], 0
	v_mov_b64_e32 v[32:33], 0
	v_mov_b64_e32 v[34:35], 0
	v_mov_b64_e32 v[36:37], 0
	v_mov_b64_e32 v[38:39], 0
	v_mov_b64_e32 v[40:41], 0
	v_mov_b64_e32 v[42:43], 0
	v_mov_b64_e32 v[44:45], 0
	v_mov_b64_e32 v[46:47], 0
	v_mov_b64_e32 v[48:49], 0
	v_mov_b64_e32 v[50:51], 0
	v_mov_b64_e32 v[52:53], 0
	v_mov_b64_e32 v[54:55], 0
	v_mov_b64_e32 v[56:57], 0
	v_mov_b64_e32 v[58:59], 0
	v_mov_b64_e32 v[60:61], 0
	v_mov_b64_e32 v[62:63], 0
	v_mov_b64_e32 v[64:65], 0
	v_mov_b64_e32 v[66:67], 0
	v_mov_b64_e32 v[68:69], 0
	v_mov_b64_e32 v[70:71], 0
	v_mov_b64_e32 v[72:73], 0
	v_mov_b64_e32 v[74:75], 0
	v_mov_b64_e32 v[76:77], 0
	v_mov_b64_e32 v[78:79], 0
	v_mov_b64_e32 v[80:81], 0
	v_mov_b64_e32 v[82:83], 0
	v_mov_b64_e32 v[84:85], 0
	v_mov_b64_e32 v[86:87], 0
	v_mov_b64_e32 v[88:89], 0
	v_mov_b64_e32 v[90:91], 0
	v_mov_b64_e32 v[92:93], 0
	v_mov_b64_e32 v[94:95], 0
	v_mov_b64_e32 v[96:97], 0
	v_mov_b64_e32 v[98:99], 0
	v_mov_b64_e32 v[100:101], 0
	v_mov_b64_e32 v[102:103], 0
	v_mov_b64_e32 v[104:105], 0
	v_mov_b64_e32 v[106:107], 0
	v_mov_b64_e32 v[108:109], 0
	v_mov_b64_e32 v[110:111], 0
	v_mov_b64_e32 v[112:113], 0
	v_mov_b64_e32 v[114:115], 0
	v_mov_b64_e32 v[116:117], 0
	v_mov_b64_e32 v[118:119], 0
	v_mov_b64_e32 v[120:121], 0
	v_mov_b64_e32 v[122:123], 0
	v_mov_b64_e32 v[124:125], 0
	v_mov_b64_e32 v[126:127], 0
	v_mov_b64_e32 v[128:129], 0
	s_and_b64 vcc, exec, s[82:83]
	s_cbranch_vccnz .Lg159_prio_skip
	s_setprio 1
.Lg159_prio_skip:
.LBB0_159:
	s_add_i32 s44, s35, 2
	s_add_u32 s42, s16, 0x80
	s_addc_u32 s43, s17, 0
	s_add_i32 s45, 0, 0x10000
	s_cmp_eq_u32 s5, s35
	s_cselect_b32 s43, s15, s43
	s_cselect_b32 s42, s14, s42
	v_add_u32_e32 v0, s45, v165
	s_cselect_b32 s47, s71, s21
	s_cselect_b32 s46, s70, s20
	s_add_i32 s35, 0, 0x14000
	ds_read_b128 v[148:151], v0
	ds_read_b128 v[152:155], v0 offset:1024
	ds_read_b128 v[156:159], v0 offset:2048
	ds_read_b128 v[160:163], v0 offset:3072
	v_add_u32_e32 v0, s35, v165
	ds_read_b128 v[168:171], v0
	ds_read_b128 v[172:175], v0 offset:1024
	ds_read_b128 v[176:179], v0 offset:2048
	ds_read_b128 v[180:183], v0 offset:3072
	v_lshl_add_u64 v[220:221], s[16:17], 0, v[144:145]
	s_add_i32 m0, s25, 0xc000
	ds_read_b128 v[184:187], v167
	ds_read_b128 v[188:191], v167 offset:1024
	ds_read_b128 v[192:195], v167 offset:2048
	ds_read_b128 v[196:199], v167 offset:3072
	ds_read_b128 v[200:203], v167 offset:4096
	ds_read_b128 v[204:207], v167 offset:5120
	ds_read_b128 v[224:227], v167 offset:6144
	ds_read_b128 v[228:231], v167 offset:7168
	global_load_lds_dwordx4 v[220:221], off
	v_lshl_add_u64 v[220:221], s[16:17], 0, v[146:147]
	s_add_i32 m0, s25, 0xe000
	s_nop 0
	global_load_lds_dwordx4 v[220:221], off
	s_waitcnt vmcnt(8)
	s_waitcnt lgkmcnt(0)
	s_barrier
	s_waitcnt lgkmcnt(0)
	v_mfma_f32_16x16x32_bf16 v[122:125], v[148:151], v[184:187], v[122:125]
	v_mfma_f32_16x16x32_bf16 v[126:129], v[156:159], v[184:187], v[126:129]
	v_mfma_f32_16x16x32_bf16 v[110:113], v[148:151], v[192:195], v[110:113]
	v_mfma_f32_16x16x32_bf16 v[106:109], v[156:159], v[192:195], v[106:109]
	v_mfma_f32_16x16x32_bf16 v[94:97], v[148:151], v[200:203], v[94:97]
	v_mfma_f32_16x16x32_bf16 v[90:93], v[156:159], v[200:203], v[90:93]
	v_mfma_f32_16x16x32_bf16 v[78:81], v[148:151], v[224:227], v[78:81]
	v_mfma_f32_16x16x32_bf16 v[74:77], v[156:159], v[224:227], v[74:77]
	v_mfma_f32_16x16x32_bf16 v[122:125], v[152:155], v[188:191], v[122:125]
	v_mfma_f32_16x16x32_bf16 v[126:129], v[160:163], v[188:191], v[126:129]
	v_mfma_f32_16x16x32_bf16 v[110:113], v[152:155], v[196:199], v[110:113]
	v_mfma_f32_16x16x32_bf16 v[106:109], v[160:163], v[196:199], v[106:109]
	v_mfma_f32_16x16x32_bf16 v[94:97], v[152:155], v[204:207], v[94:97]
	v_mfma_f32_16x16x32_bf16 v[90:93], v[160:163], v[204:207], v[90:93]
	v_mfma_f32_16x16x32_bf16 v[78:81], v[152:155], v[228:231], v[78:81]
	v_mfma_f32_16x16x32_bf16 v[74:77], v[160:163], v[228:231], v[74:77]
	v_mfma_f32_16x16x32_bf16 v[118:121], v[168:171], v[184:187], v[118:121]
	v_mfma_f32_16x16x32_bf16 v[114:117], v[176:179], v[184:187], v[114:117]
	v_mfma_f32_16x16x32_bf16 v[102:105], v[168:171], v[192:195], v[102:105]
	v_mfma_f32_16x16x32_bf16 v[98:101], v[176:179], v[192:195], v[98:101]
	v_mfma_f32_16x16x32_bf16 v[86:89], v[168:171], v[200:203], v[86:89]
	v_mfma_f32_16x16x32_bf16 v[82:85], v[176:179], v[200:203], v[82:85]
	v_mfma_f32_16x16x32_bf16 v[70:73], v[168:171], v[224:227], v[70:73]
	v_mfma_f32_16x16x32_bf16 v[66:69], v[176:179], v[224:227], v[66:69]
	v_mfma_f32_16x16x32_bf16 v[118:121], v[172:175], v[188:191], v[118:121]
	v_mfma_f32_16x16x32_bf16 v[114:117], v[180:183], v[188:191], v[114:117]
	v_mfma_f32_16x16x32_bf16 v[102:105], v[172:175], v[196:199], v[102:105]
	v_mfma_f32_16x16x32_bf16 v[98:101], v[180:183], v[196:199], v[98:101]
	v_mfma_f32_16x16x32_bf16 v[86:89], v[172:175], v[204:207], v[86:89]
	v_mfma_f32_16x16x32_bf16 v[82:85], v[180:183], v[204:207], v[82:85]
	v_mfma_f32_16x16x32_bf16 v[70:73], v[172:175], v[228:231], v[70:73]
	v_mfma_f32_16x16x32_bf16 v[66:69], v[180:183], v[228:231], v[66:69]
	s_barrier
; #define PG8_STAGE(bufoff, gbase, voff) do { _Pragma("unroll") for (int _i = 0; _i < 2; ++_i) \
;         __builtin_amdgcn_global_load_lds((const unsigned*)((const char*)(gbase) + (voff)[_i]), (LAS unsigned*)(lds + (bufoff) + ldsw + _i * 8192), 16, 0, 0); } while (0)
; #define PG8_LDA(dst, b, h) do { _Pragma("unroll") for (int m = 0; m < 4; ++m) _Pragma("unroll") for (int k = 0; k < 2; ++k) dst[m][k] = *(const LAS bf16x8*)(lds + PG8_SA(b, h) + aoff + m * 2048 + k * 1024); } while (0)
; #define PG8_LDB(dst, b, h) do { _Pragma("unroll") for (int n = 0; n < 2; ++n) _Pragma("unroll") for (int k = 0; k < 2; ++k) dst[n][k] = *(const LAS bf16x8*)(lds + PG8_SB(b, h) + boff + n * 2048 + k * 1024); } while (0)
; #define PG8_MMA(ai, bj, At, Bt) do { __builtin_amdgcn_s_setprio(1); _Pragma("unroll") for (int m = 0; m < 4; ++m) _Pragma("unroll") for (int n = 0; n < 2; ++n) _Pragma("unroll") for (int k = 0; k < 2; ++k) \
;         acc[ai][bj][m][n] = __builtin_amdgcn_mfma_f32_16x16x32_bf16(Bt[n][k], At[m][k], acc[ai][bj][m][n], 0, 0, 0); __builtin_amdgcn_s_setprio(0); } while (0)
; #define PG8_WAIT_V(n) asm volatile("s_waitcnt vmcnt(" #n ")" ::: "memory")
; #define PG8_WAIT_L(n) asm volatile("s_waitcnt lgkmcnt(" #n ")" ::: "memory")
; #define PG8_BAR __builtin_amdgcn_s_barrier()
; #define PG8_SCHED __builtin_amdgcn_sched_barrier(0)
; template <class Epi>
; __device__ __forceinline__ void gemm_phase(LAS unsigned char* lds, const Gemm g, const Epi& E) {
;     ...
;             PG8_WAIT_V(8); PG8_WAIT_L(0); PG8_BAR; PG8_MMA(0, 0, At, B0); PG8_MMA(0, 1, At, B1); PG8_BAR; PG8_SCHED;
;             PG8_LDA(At, 0, 1); PG8_STAGE(PG8_SB(0, 0), b2, voffB); PG8_STAGE(PG8_SB(0, 1), b2 + hstepB, voffB); PG8_STAGE(PG8_SA(0, 0), a2, voffA);
;             PG8_WAIT_V(8); PG8_WAIT_L(0); PG8_BAR; PG8_MMA(1, 0, At, B0); PG8_MMA(1, 1, At, B1); PG8_BAR; PG8_SCHED;
;             PG8_LDB(B0, 1, 0); PG8_LDB(B1, 1, 1); PG8_SCHED; PG8_LDA(At, 1, 0); PG8_STAGE(PG8_SA(0, 1), a2 + hstepA, voffA);
;             PG8_WAIT_V(8); PG8_WAIT_L(0); PG8_BAR; PG8_MMA(0, 0, At, B0); PG8_MMA(0, 1, At, B1); PG8_BAR; PG8_SCHED;
	s_add_i32 s45, s45, s24
	v_lshl_add_u64 v[220:221], s[46:47], 0, v[134:135]
	s_mov_b32 m0, s45
	ds_read_b128 v[184:187], v167 offset:16384
	ds_read_b128 v[188:191], v167 offset:17408
	ds_read_b128 v[192:195], v167 offset:18432
	ds_read_b128 v[196:199], v167 offset:19456
	ds_read_b128 v[200:203], v167 offset:20480
	ds_read_b128 v[204:207], v167 offset:21504
	ds_read_b128 v[224:227], v167 offset:22528
	ds_read_b128 v[228:231], v167 offset:23552
	global_load_lds_dwordx4 v[220:221], off
	s_add_i32 m0, s45, 0x2000
	v_lshl_add_u64 v[222:223], s[46:47], 0, v[130:131]
	s_add_u32 s46, s46, s62
	s_addc_u32 s47, s47, s63
	s_add_i32 s35, s35, s24
	global_load_lds_dwordx4 v[222:223], off
	v_lshl_add_u64 v[232:233], s[46:47], 0, v[134:135]
	s_mov_b32 m0, s35
	v_lshl_add_u64 v[242:243], s[46:47], 0, v[130:131]
	global_load_lds_dwordx4 v[232:233], off
	s_add_i32 m0, s35, 0x2000
	v_lshl_add_u64 v[244:245], s[42:43], 0, v[136:137]
	global_load_lds_dwordx4 v[242:243], off
	s_mov_b32 m0, s25
	v_lshl_add_u64 v[246:247], s[42:43], 0, v[132:133]
	global_load_lds_dwordx4 v[244:245], off
	s_mov_b32 m0, s54
	s_nop 0
	global_load_lds_dwordx4 v[246:247], off
	s_waitcnt vmcnt(8)
	s_waitcnt lgkmcnt(0)
	s_barrier
	s_waitcnt lgkmcnt(0)
	v_mfma_f32_16x16x32_bf16 v[62:65], v[148:151], v[184:187], v[62:65]
	v_mfma_f32_16x16x32_bf16 v[58:61], v[156:159], v[184:187], v[58:61]
	v_mfma_f32_16x16x32_bf16 v[46:49], v[148:151], v[192:195], v[46:49]
	v_mfma_f32_16x16x32_bf16 v[42:45], v[156:159], v[192:195], v[42:45]
	v_mfma_f32_16x16x32_bf16 v[30:33], v[148:151], v[200:203], v[30:33]
	v_mfma_f32_16x16x32_bf16 v[26:29], v[156:159], v[200:203], v[26:29]
	v_mfma_f32_16x16x32_bf16 v[14:17], v[148:151], v[224:227], v[14:17]
	v_mfma_f32_16x16x32_bf16 v[10:13], v[156:159], v[224:227], v[10:13]
	v_mfma_f32_16x16x32_bf16 v[62:65], v[152:155], v[188:191], v[62:65]
	v_mfma_f32_16x16x32_bf16 v[58:61], v[160:163], v[188:191], v[58:61]
	v_mfma_f32_16x16x32_bf16 v[46:49], v[152:155], v[196:199], v[46:49]
	v_mfma_f32_16x16x32_bf16 v[42:45], v[160:163], v[196:199], v[42:45]
	v_mfma_f32_16x16x32_bf16 v[30:33], v[152:155], v[204:207], v[30:33]
	v_mfma_f32_16x16x32_bf16 v[26:29], v[160:163], v[204:207], v[26:29]
	v_mfma_f32_16x16x32_bf16 v[14:17], v[152:155], v[228:231], v[14:17]
	v_mfma_f32_16x16x32_bf16 v[10:13], v[160:163], v[228:231], v[10:13]
	v_mfma_f32_16x16x32_bf16 v[54:57], v[168:171], v[184:187], v[54:57]
	v_mfma_f32_16x16x32_bf16 v[50:53], v[176:179], v[184:187], v[50:53]
	v_mfma_f32_16x16x32_bf16 v[38:41], v[168:171], v[192:195], v[38:41]
	v_mfma_f32_16x16x32_bf16 v[34:37], v[176:179], v[192:195], v[34:37]
	v_mfma_f32_16x16x32_bf16 v[22:25], v[168:171], v[200:203], v[22:25]
	v_mfma_f32_16x16x32_bf16 v[18:21], v[176:179], v[200:203], v[18:21]
	v_mfma_f32_16x16x32_bf16 v[6:9], v[168:171], v[224:227], v[6:9]
	v_mfma_f32_16x16x32_bf16 v[2:5], v[176:179], v[224:227], v[2:5]
	v_mfma_f32_16x16x32_bf16 v[54:57], v[172:175], v[188:191], v[54:57]
	v_mfma_f32_16x16x32_bf16 v[50:53], v[180:183], v[188:191], v[50:53]
	v_mfma_f32_16x16x32_bf16 v[38:41], v[172:175], v[196:199], v[38:41]
	v_mfma_f32_16x16x32_bf16 v[34:37], v[180:183], v[196:199], v[34:37]
	v_mfma_f32_16x16x32_bf16 v[22:25], v[172:175], v[204:207], v[22:25]
	v_mfma_f32_16x16x32_bf16 v[18:21], v[180:183], v[204:207], v[18:21]
	v_mfma_f32_16x16x32_bf16 v[6:9], v[172:175], v[228:231], v[6:9]
	v_mfma_f32_16x16x32_bf16 v[2:5], v[180:183], v[228:231], v[2:5]
	s_barrier
	s_add_i32 s35, 0, 0x18000
	v_add_u32_e32 v0, s35, v165
	s_add_i32 s45, 0, 0x1c000
	ds_read_b128 v[148:151], v0
	ds_read_b128 v[152:155], v0 offset:1024
	ds_read_b128 v[156:159], v0 offset:2048
	ds_read_b128 v[160:163], v0 offset:3072
	v_add_u32_e32 v0, s45, v165
	ds_read_b128 v[168:171], v0
	ds_read_b128 v[172:175], v0 offset:1024
	ds_read_b128 v[176:179], v0 offset:2048
	ds_read_b128 v[180:183], v0 offset:3072
	s_add_u32 s42, s42, s52
	s_addc_u32 s43, s43, s53
	s_mov_b32 m0, s55
	v_lshl_add_u64 v[248:249], s[42:43], 0, v[136:137]
	ds_read_b128 v[184:187], v167 offset:32768
	ds_read_b128 v[188:191], v167 offset:33792
	ds_read_b128 v[192:195], v167 offset:34816
	ds_read_b128 v[196:199], v167 offset:35840
	ds_read_b128 v[200:203], v167 offset:36864
	ds_read_b128 v[204:207], v167 offset:37888
	ds_read_b128 v[224:227], v167 offset:38912
	ds_read_b128 v[228:231], v167 offset:39936
	global_load_lds_dwordx4 v[248:249], off
	v_lshl_add_u64 v[248:249], s[42:43], 0, v[132:133]
	s_mov_b32 m0, s58
	s_nop 0
	global_load_lds_dwordx4 v[248:249], off
	s_waitcnt vmcnt(8)
	s_waitcnt lgkmcnt(0)
	s_barrier
; #define PG8_STAGE(bufoff, gbase, voff) do { _Pragma("unroll") for (int _i = 0; _i < 2; ++_i) \
;         __builtin_amdgcn_global_load_lds((const unsigned*)((const char*)(gbase) + (voff)[_i]), (LAS unsigned*)(lds + (bufoff) + ldsw + _i * 8192), 16, 0, 0); } while (0)
; #define PG8_LDA(dst, b, h) do { _Pragma("unroll") for (int m = 0; m < 4; ++m) _Pragma("unroll") for (int k = 0; k < 2; ++k) dst[m][k] = *(const LAS bf16x8*)(lds + PG8_SA(b, h) + aoff + m * 2048 + k * 1024); } while (0)
; #define PG8_MMA(ai, bj, At, Bt) do { __builtin_amdgcn_s_setprio(1); _Pragma("unroll") for (int m = 0; m < 4; ++m) _Pragma("unroll") for (int n = 0; n < 2; ++n) _Pragma("unroll") for (int k = 0; k < 2; ++k) \
;         acc[ai][bj][m][n] = __builtin_amdgcn_mfma_f32_16x16x32_bf16(Bt[n][k], At[m][k], acc[ai][bj][m][n], 0, 0, 0); __builtin_amdgcn_s_setprio(0); } while (0)
; #define PG8_WAIT_V(n) asm volatile("s_waitcnt vmcnt(" #n ")" ::: "memory")
; #define PG8_WAIT_L(n) asm volatile("s_waitcnt lgkmcnt(" #n ")" ::: "memory")
; #define PG8_BAR __builtin_amdgcn_s_barrier()
; #define PG8_SCHED __builtin_amdgcn_sched_barrier(0)
; template <class Epi>
; __device__ __forceinline__ void gemm_phase(LAS unsigned char* lds, const Gemm g, const Epi& E) {
;     ...
;             PG8_WAIT_V(8); PG8_WAIT_L(0); PG8_BAR; PG8_MMA(0, 0, At, B0); PG8_MMA(0, 1, At, B1); PG8_BAR; PG8_SCHED;
;             PG8_LDA(At, 1, 1); PG8_STAGE(PG8_SB(1, 0), b3, voffB); PG8_STAGE(PG8_SB(1, 1), b3 + hstepB, voffB); PG8_STAGE(PG8_SA(1, 0), a3, voffA);
;             PG8_WAIT_V(8); PG8_WAIT_L(0); PG8_BAR; PG8_MMA(1, 0, At, B0); PG8_MMA(1, 1, At, B1); PG8_BAR; PG8_SCHED;
;         }
	s_waitcnt lgkmcnt(0)
	v_mfma_f32_16x16x32_bf16 v[122:125], v[148:151], v[184:187], v[122:125]
	v_mfma_f32_16x16x32_bf16 v[126:129], v[156:159], v[184:187], v[126:129]
	v_mfma_f32_16x16x32_bf16 v[110:113], v[148:151], v[192:195], v[110:113]
	v_mfma_f32_16x16x32_bf16 v[106:109], v[156:159], v[192:195], v[106:109]
	v_mfma_f32_16x16x32_bf16 v[94:97], v[148:151], v[200:203], v[94:97]
	v_mfma_f32_16x16x32_bf16 v[90:93], v[156:159], v[200:203], v[90:93]
	v_mfma_f32_16x16x32_bf16 v[78:81], v[148:151], v[224:227], v[78:81]
	v_mfma_f32_16x16x32_bf16 v[74:77], v[156:159], v[224:227], v[74:77]
	v_mfma_f32_16x16x32_bf16 v[122:125], v[152:155], v[188:191], v[122:125]
	v_mfma_f32_16x16x32_bf16 v[126:129], v[160:163], v[188:191], v[126:129]
	v_mfma_f32_16x16x32_bf16 v[110:113], v[152:155], v[196:199], v[110:113]
	v_mfma_f32_16x16x32_bf16 v[106:109], v[160:163], v[196:199], v[106:109]
	v_mfma_f32_16x16x32_bf16 v[94:97], v[152:155], v[204:207], v[94:97]
	v_mfma_f32_16x16x32_bf16 v[90:93], v[160:163], v[204:207], v[90:93]
	v_mfma_f32_16x16x32_bf16 v[78:81], v[152:155], v[228:231], v[78:81]
	v_mfma_f32_16x16x32_bf16 v[74:77], v[160:163], v[228:231], v[74:77]
	v_mfma_f32_16x16x32_bf16 v[118:121], v[168:171], v[184:187], v[118:121]
	v_mfma_f32_16x16x32_bf16 v[114:117], v[176:179], v[184:187], v[114:117]
	v_mfma_f32_16x16x32_bf16 v[102:105], v[168:171], v[192:195], v[102:105]
	v_mfma_f32_16x16x32_bf16 v[98:101], v[176:179], v[192:195], v[98:101]
	v_mfma_f32_16x16x32_bf16 v[86:89], v[168:171], v[200:203], v[86:89]
	v_mfma_f32_16x16x32_bf16 v[82:85], v[176:179], v[200:203], v[82:85]
	v_mfma_f32_16x16x32_bf16 v[70:73], v[168:171], v[224:227], v[70:73]
	v_mfma_f32_16x16x32_bf16 v[66:69], v[176:179], v[224:227], v[66:69]
	v_mfma_f32_16x16x32_bf16 v[118:121], v[172:175], v[188:191], v[118:121]
	v_mfma_f32_16x16x32_bf16 v[114:117], v[180:183], v[188:191], v[114:117]
	v_mfma_f32_16x16x32_bf16 v[102:105], v[172:175], v[196:199], v[102:105]
	v_mfma_f32_16x16x32_bf16 v[98:101], v[180:183], v[196:199], v[98:101]
	v_mfma_f32_16x16x32_bf16 v[86:89], v[172:175], v[204:207], v[86:89]
	v_mfma_f32_16x16x32_bf16 v[82:85], v[180:183], v[204:207], v[82:85]
	v_mfma_f32_16x16x32_bf16 v[70:73], v[172:175], v[228:231], v[70:73]
	v_mfma_f32_16x16x32_bf16 v[66:69], v[180:183], v[228:231], v[66:69]
	s_barrier
	s_add_i32 s35, s35, s24
	v_lshl_add_u64 v[220:221], v[220:221], 0, s[28:29]
	s_mov_b32 m0, s35
	ds_read_b128 v[184:187], v167 offset:49152
	ds_read_b128 v[188:191], v167 offset:50176
	ds_read_b128 v[192:195], v167 offset:51200
	ds_read_b128 v[196:199], v167 offset:52224
	ds_read_b128 v[200:203], v167 offset:53248
	ds_read_b128 v[204:207], v167 offset:54272
	ds_read_b128 v[224:227], v167 offset:55296
	ds_read_b128 v[228:231], v167 offset:56320
	global_load_lds_dwordx4 v[220:221], off
	v_lshl_add_u64 v[220:221], v[222:223], 0, s[28:29]
	s_add_i32 m0, s35, 0x2000
	s_add_i32 s35, s45, s24
	global_load_lds_dwordx4 v[220:221], off
	v_lshl_add_u64 v[220:221], v[232:233], 0, s[28:29]
	s_mov_b32 m0, s35
	s_nop 0
	global_load_lds_dwordx4 v[220:221], off
	v_lshl_add_u64 v[220:221], v[242:243], 0, s[28:29]
	s_add_i32 m0, s35, 0x2000
	s_nop 0
	global_load_lds_dwordx4 v[220:221], off
	v_lshl_add_u64 v[220:221], v[244:245], 0, s[28:29]
	s_mov_b32 m0, s59
	s_nop 0
	global_load_lds_dwordx4 v[220:221], off
	v_lshl_add_u64 v[220:221], v[246:247], 0, s[28:29]
	s_mov_b32 m0, s61
	s_nop 0
	global_load_lds_dwordx4 v[220:221], off
	s_waitcnt vmcnt(8)
	s_waitcnt lgkmcnt(0)
	s_barrier
	s_waitcnt lgkmcnt(0)
	v_mfma_f32_16x16x32_bf16 v[62:65], v[148:151], v[184:187], v[62:65]
	v_mfma_f32_16x16x32_bf16 v[58:61], v[156:159], v[184:187], v[58:61]
	v_mfma_f32_16x16x32_bf16 v[46:49], v[148:151], v[192:195], v[46:49]
	v_mfma_f32_16x16x32_bf16 v[42:45], v[156:159], v[192:195], v[42:45]
	v_mfma_f32_16x16x32_bf16 v[30:33], v[148:151], v[200:203], v[30:33]
	v_mfma_f32_16x16x32_bf16 v[26:29], v[156:159], v[200:203], v[26:29]
	v_mfma_f32_16x16x32_bf16 v[14:17], v[148:151], v[224:227], v[14:17]
	v_mfma_f32_16x16x32_bf16 v[10:13], v[156:159], v[224:227], v[10:13]
	v_mfma_f32_16x16x32_bf16 v[62:65], v[152:155], v[188:191], v[62:65]
	v_mfma_f32_16x16x32_bf16 v[58:61], v[160:163], v[188:191], v[58:61]
	v_mfma_f32_16x16x32_bf16 v[46:49], v[152:155], v[196:199], v[46:49]
	v_mfma_f32_16x16x32_bf16 v[42:45], v[160:163], v[196:199], v[42:45]
	v_mfma_f32_16x16x32_bf16 v[30:33], v[152:155], v[204:207], v[30:33]
	v_mfma_f32_16x16x32_bf16 v[26:29], v[160:163], v[204:207], v[26:29]
	v_mfma_f32_16x16x32_bf16 v[14:17], v[152:155], v[228:231], v[14:17]
	v_mfma_f32_16x16x32_bf16 v[10:13], v[160:163], v[228:231], v[10:13]
	v_mfma_f32_16x16x32_bf16 v[54:57], v[168:171], v[184:187], v[54:57]
	v_mfma_f32_16x16x32_bf16 v[50:53], v[176:179], v[184:187], v[50:53]
	v_mfma_f32_16x16x32_bf16 v[38:41], v[168:171], v[192:195], v[38:41]
	v_mfma_f32_16x16x32_bf16 v[34:37], v[176:179], v[192:195], v[34:37]
	v_mfma_f32_16x16x32_bf16 v[22:25], v[168:171], v[200:203], v[22:25]
	v_mfma_f32_16x16x32_bf16 v[18:21], v[176:179], v[200:203], v[18:21]
	v_mfma_f32_16x16x32_bf16 v[6:9], v[168:171], v[224:227], v[6:9]
	v_mfma_f32_16x16x32_bf16 v[2:5], v[176:179], v[224:227], v[2:5]
	v_mfma_f32_16x16x32_bf16 v[54:57], v[172:175], v[188:191], v[54:57]
	v_mfma_f32_16x16x32_bf16 v[50:53], v[180:183], v[188:191], v[50:53]
	v_mfma_f32_16x16x32_bf16 v[38:41], v[172:175], v[196:199], v[38:41]
	v_mfma_f32_16x16x32_bf16 v[34:37], v[180:183], v[196:199], v[34:37]
	v_mfma_f32_16x16x32_bf16 v[22:25], v[172:175], v[204:207], v[22:25]
	v_mfma_f32_16x16x32_bf16 v[18:21], v[180:183], v[204:207], v[18:21]
	v_mfma_f32_16x16x32_bf16 v[6:9], v[172:175], v[228:231], v[6:9]
	v_mfma_f32_16x16x32_bf16 v[2:5], v[180:183], v[228:231], v[2:5]
	s_barrier
	s_add_u32 s16, s16, 0x100
	s_addc_u32 s17, s17, 0
	s_add_u32 s20, s20, 0x100
	s_addc_u32 s21, s21, 0
	s_cmp_ge_i32 s44, s6
	s_mov_b32 s35, s44
	s_cbranch_scc0 .LBB0_159
	s_setprio 0

; #define PG8_STAGE(bufoff, gbase, voff) do { _Pragma("unroll") for (int _i = 0; _i < 2; ++_i) \
;         __builtin_amdgcn_global_load_lds((const unsigned*)((const char*)(gbase) + (voff)[_i]), (LAS unsigned*)(lds + (bufoff) + ldsw + _i * 8192), 16, 0, 0); } while (0)
; #define PG8_LDA(dst, b, h) do { _Pragma("unroll") for (int m = 0; m < 4; ++m) _Pragma("unroll") for (int k = 0; k < 2; ++k) dst[m][k] = *(const LAS bf16x8*)(lds + PG8_SA(b, h) + aoff + m * 2048 + k * 1024); } while (0)
; #define PG8_LDB(dst, b, h) do { _Pragma("unroll") for (int n = 0; n < 2; ++n) _Pragma("unroll") for (int k = 0; k < 2; ++k) dst[n][k] = *(const LAS bf16x8*)(lds + PG8_SB(b, h) + boff + n * 2048 + k * 1024); } while (0)
; #define PG8_MMA(ai, bj, At, Bt) do { __builtin_amdgcn_s_setprio(1); _Pragma("unroll") for (int m = 0; m < 4; ++m) _Pragma("unroll") for (int n = 0; n < 2; ++n) _Pragma("unroll") for (int k = 0; k < 2; ++k) \
;         acc[ai][bj][m][n] = __builtin_amdgcn_mfma_f32_16x16x32_bf16(Bt[n][k], At[m][k], acc[ai][bj][m][n], 0, 0, 0); __builtin_amdgcn_s_setprio(0); } while (0)
; #define PG8_WAIT_V(n) asm volatile("s_waitcnt vmcnt(" #n ")" ::: "memory")
; #define PG8_WAIT_L(n) asm volatile("s_waitcnt lgkmcnt(" #n ")" ::: "memory")
; #define PG8_BAR __builtin_amdgcn_s_barrier()
; #define PG8_SCHED __builtin_amdgcn_sched_barrier(0)
; template <class Epi>
; __device__ __forceinline__ void gemm_phase(LAS unsigned char* lds, const Gemm g, const Epi& E) {
;     ...
;             PG8_LDB(B0, 0, 0); PG8_LDB(B1, 0, 1); PG8_SCHED; PG8_LDA(At, 0, 0); PG8_STAGE(PG8_SA(1, 1), a1 + hstepA, voffA);
;             PG8_WAIT_V(8); PG8_WAIT_L(0); PG8_BAR; PG8_MMA(0, 0, At, B0); PG8_MMA(0, 1, At, B1); PG8_BAR; PG8_SCHED;
;     ...
;         for (int a = 0; a < 2; ++a)
; #pragma unroll
;             for (int b = 0; b < 2; ++b)
; #pragma unroll
;                 for (int m = 0; m < 4; ++m)
; #pragma unroll
;                     for (int n = 0; n < 2; ++n) acc[a][b][m][n] = (f32x4){0.f, 0.f, 0.f, 0.f};
.Luq_ssq_skip:
	s_add_u32 s0, s0, 0x80
	s_addc_u32 s1, s1, 0
	s_add_u32 s6, s10, 0x100
	s_addc_u32 s7, s11, 0
	s_mov_b32 s8, 0
	v_mov_b64_e32 v[2:3], 0
	v_mov_b64_e32 v[4:5], 0
	v_mov_b64_e32 v[6:7], 0
	v_mov_b64_e32 v[8:9], 0
	v_mov_b64_e32 v[10:11], 0
	v_mov_b64_e32 v[12:13], 0
	v_mov_b64_e32 v[14:15], 0
	v_mov_b64_e32 v[16:17], 0
	v_mov_b64_e32 v[18:19], 0
	v_mov_b64_e32 v[20:21], 0
	v_mov_b64_e32 v[22:23], 0
	v_mov_b64_e32 v[24:25], 0
	v_mov_b64_e32 v[26:27], 0
	v_mov_b64_e32 v[28:29], 0
	v_mov_b64_e32 v[30:31], 0
	v_mov_b64_e32 v[32:33], 0
	v_mov_b64_e32 v[34:35], 0
	v_mov_b64_e32 v[36:37], 0
	v_mov_b64_e32 v[38:39], 0
	v_mov_b64_e32 v[40:41], 0
	v_mov_b64_e32 v[42:43], 0
	v_mov_b64_e32 v[44:45], 0
	v_mov_b64_e32 v[46:47], 0
	v_mov_b64_e32 v[48:49], 0
	v_mov_b64_e32 v[50:51], 0
	v_mov_b64_e32 v[52:53], 0
	v_mov_b64_e32 v[54:55], 0
	v_mov_b64_e32 v[56:57], 0
	v_mov_b64_e32 v[58:59], 0
	v_mov_b64_e32 v[60:61], 0
	v_mov_b64_e32 v[62:63], 0
	v_mov_b64_e32 v[64:65], 0
	v_mov_b64_e32 v[66:67], 0
	v_mov_b64_e32 v[68:69], 0
	v_mov_b64_e32 v[70:71], 0
	v_mov_b64_e32 v[72:73], 0
	v_mov_b64_e32 v[74:75], 0
	v_mov_b64_e32 v[76:77], 0
	v_mov_b64_e32 v[78:79], 0
	v_mov_b64_e32 v[80:81], 0
	v_mov_b64_e32 v[82:83], 0
	v_mov_b64_e32 v[84:85], 0
	v_mov_b64_e32 v[86:87], 0
	v_mov_b64_e32 v[88:89], 0
	v_mov_b64_e32 v[90:91], 0
	v_mov_b64_e32 v[92:93], 0
	v_mov_b64_e32 v[94:95], 0
	v_mov_b64_e32 v[96:97], 0
	v_mov_b64_e32 v[98:99], 0
	v_mov_b64_e32 v[100:101], 0
	v_mov_b64_e32 v[102:103], 0
	v_mov_b64_e32 v[104:105], 0
	v_mov_b64_e32 v[106:107], 0
	v_mov_b64_e32 v[108:109], 0
	v_mov_b64_e32 v[110:111], 0
	v_mov_b64_e32 v[112:113], 0
	v_mov_b64_e32 v[114:115], 0
	v_mov_b64_e32 v[116:117], 0
	v_mov_b64_e32 v[118:119], 0
	v_mov_b64_e32 v[120:121], 0
	v_mov_b64_e32 v[122:123], 0
	v_mov_b64_e32 v[124:125], 0
	v_mov_b64_e32 v[126:127], 0
	v_mov_b64_e32 v[128:129], 0
	s_and_b64 vcc, exec, s[80:81]
	s_cbranch_vccnz .Lg328_prio_skip
	s_setprio 1
.Lg328_prio_skip:
.LBB0_328:
	s_add_i32 s9, s8, 2
	s_add_u32 s10, s0, 0x80
	s_addc_u32 s11, s1, 0
	s_add_i32 s18, 0, 0x10000
	s_cmp_eq_u32 s70, s8
	s_cselect_b32 s11, s83, s11
	s_cselect_b32 s10, s82, s10
	v_add_u32_e32 v0, s18, v171
	s_cselect_b32 s15, s75, s7
	s_cselect_b32 s14, s74, s6
	s_add_i32 s8, 0, 0x14000
	ds_read_b128 v[130:133], v0
	ds_read_b128 v[134:137], v0 offset:1024
	ds_read_b128 v[156:159], v0 offset:2048
	ds_read_b128 v[160:163], v0 offset:3072
	v_add_u32_e32 v0, s8, v171
	ds_read_b128 v[164:167], v0
	ds_read_b128 v[174:177], v0 offset:1024
	ds_read_b128 v[178:181], v0 offset:2048
	ds_read_b128 v[182:185], v0 offset:3072
	v_lshl_add_u64 v[168:169], s[0:1], 0, v[152:153]
	s_add_i32 m0, s21, 0xc000
	ds_read_b128 v[186:189], v173
	ds_read_b128 v[190:193], v173 offset:1024
	ds_read_b128 v[194:197], v173 offset:2048
	ds_read_b128 v[198:201], v173 offset:3072
	ds_read_b128 v[202:205], v173 offset:4096
	ds_read_b128 v[224:227], v173 offset:5120
	ds_read_b128 v[228:231], v173 offset:6144
	ds_read_b128 v[242:245], v173 offset:7168
	global_load_lds_dwordx4 v[168:169], off
	v_lshl_add_u64 v[168:169], s[0:1], 0, v[154:155]
	s_add_i32 m0, s21, 0xe000
	s_nop 0
	global_load_lds_dwordx4 v[168:169], off
	s_waitcnt vmcnt(8)
	s_waitcnt lgkmcnt(0)
	s_barrier
	s_waitcnt lgkmcnt(0)
	v_mfma_f32_16x16x32_bf16 v[122:125], v[130:133], v[186:189], v[122:125]
	v_mfma_f32_16x16x32_bf16 v[126:129], v[156:159], v[186:189], v[126:129]
	v_mfma_f32_16x16x32_bf16 v[110:113], v[130:133], v[194:197], v[110:113]
	v_mfma_f32_16x16x32_bf16 v[106:109], v[156:159], v[194:197], v[106:109]
	v_mfma_f32_16x16x32_bf16 v[94:97], v[130:133], v[202:205], v[94:97]
	v_mfma_f32_16x16x32_bf16 v[90:93], v[156:159], v[202:205], v[90:93]
	v_mfma_f32_16x16x32_bf16 v[78:81], v[130:133], v[228:231], v[78:81]
	v_mfma_f32_16x16x32_bf16 v[74:77], v[156:159], v[228:231], v[74:77]
	v_mfma_f32_16x16x32_bf16 v[122:125], v[134:137], v[190:193], v[122:125]
	v_mfma_f32_16x16x32_bf16 v[126:129], v[160:163], v[190:193], v[126:129]
	v_mfma_f32_16x16x32_bf16 v[110:113], v[134:137], v[198:201], v[110:113]
	v_mfma_f32_16x16x32_bf16 v[106:109], v[160:163], v[198:201], v[106:109]
	v_mfma_f32_16x16x32_bf16 v[94:97], v[134:137], v[224:227], v[94:97]
	v_mfma_f32_16x16x32_bf16 v[90:93], v[160:163], v[224:227], v[90:93]
	v_mfma_f32_16x16x32_bf16 v[78:81], v[134:137], v[242:245], v[78:81]
	v_mfma_f32_16x16x32_bf16 v[74:77], v[160:163], v[242:245], v[74:77]
	v_mfma_f32_16x16x32_bf16 v[118:121], v[164:167], v[186:189], v[118:121]
	v_mfma_f32_16x16x32_bf16 v[114:117], v[178:181], v[186:189], v[114:117]
	v_mfma_f32_16x16x32_bf16 v[102:105], v[164:167], v[194:197], v[102:105]
	v_mfma_f32_16x16x32_bf16 v[98:101], v[178:181], v[194:197], v[98:101]
	v_mfma_f32_16x16x32_bf16 v[86:89], v[164:167], v[202:205], v[86:89]
	v_mfma_f32_16x16x32_bf16 v[82:85], v[178:181], v[202:205], v[82:85]
	v_mfma_f32_16x16x32_bf16 v[70:73], v[164:167], v[228:231], v[70:73]
	v_mfma_f32_16x16x32_bf16 v[66:69], v[178:181], v[228:231], v[66:69]
	v_mfma_f32_16x16x32_bf16 v[118:121], v[174:177], v[190:193], v[118:121]
	v_mfma_f32_16x16x32_bf16 v[114:117], v[182:185], v[190:193], v[114:117]
	v_mfma_f32_16x16x32_bf16 v[102:105], v[174:177], v[198:201], v[102:105]
	v_mfma_f32_16x16x32_bf16 v[98:101], v[182:185], v[198:201], v[98:101]
	v_mfma_f32_16x16x32_bf16 v[86:89], v[174:177], v[224:227], v[86:89]
	v_mfma_f32_16x16x32_bf16 v[82:85], v[182:185], v[224:227], v[82:85]
	v_mfma_f32_16x16x32_bf16 v[70:73], v[174:177], v[242:245], v[70:73]
	v_mfma_f32_16x16x32_bf16 v[66:69], v[182:185], v[242:245], v[66:69]
	s_barrier
; #define PG8_STAGE(bufoff, gbase, voff) do { _Pragma("unroll") for (int _i = 0; _i < 2; ++_i) \
;         __builtin_amdgcn_global_load_lds((const unsigned*)((const char*)(gbase) + (voff)[_i]), (LAS unsigned*)(lds + (bufoff) + ldsw + _i * 8192), 16, 0, 0); } while (0)
; #define PG8_LDA(dst, b, h) do { _Pragma("unroll") for (int m = 0; m < 4; ++m) _Pragma("unroll") for (int k = 0; k < 2; ++k) dst[m][k] = *(const LAS bf16x8*)(lds + PG8_SA(b, h) + aoff + m * 2048 + k * 1024); } while (0)
; #define PG8_LDB(dst, b, h) do { _Pragma("unroll") for (int n = 0; n < 2; ++n) _Pragma("unroll") for (int k = 0; k < 2; ++k) dst[n][k] = *(const LAS bf16x8*)(lds + PG8_SB(b, h) + boff + n * 2048 + k * 1024); } while (0)
; #define PG8_MMA(ai, bj, At, Bt) do { __builtin_amdgcn_s_setprio(1); _Pragma("unroll") for (int m = 0; m < 4; ++m) _Pragma("unroll") for (int n = 0; n < 2; ++n) _Pragma("unroll") for (int k = 0; k < 2; ++k) \
;         acc[ai][bj][m][n] = __builtin_amdgcn_mfma_f32_16x16x32_bf16(Bt[n][k], At[m][k], acc[ai][bj][m][n], 0, 0, 0); __builtin_amdgcn_s_setprio(0); } while (0)
; #define PG8_WAIT_V(n) asm volatile("s_waitcnt vmcnt(" #n ")" ::: "memory")
; #define PG8_WAIT_L(n) asm volatile("s_waitcnt lgkmcnt(" #n ")" ::: "memory")
; #define PG8_BAR __builtin_amdgcn_s_barrier()
; #define PG8_SCHED __builtin_amdgcn_sched_barrier(0)
; template <class Epi>
; __device__ __forceinline__ void gemm_phase(LAS unsigned char* lds, const Gemm g, const Epi& E) {
;     ...
;             PG8_LDA(At, 0, 1); PG8_STAGE(PG8_SB(0, 0), b2, voffB); PG8_STAGE(PG8_SB(0, 1), b2 + hstepB, voffB); PG8_STAGE(PG8_SA(0, 0), a2, voffA);
;             PG8_WAIT_V(8); PG8_WAIT_L(0); PG8_BAR; PG8_MMA(1, 0, At, B0); PG8_MMA(1, 1, At, B1); PG8_BAR; PG8_SCHED;
;             PG8_LDB(B0, 1, 0); PG8_LDB(B1, 1, 1); PG8_SCHED; PG8_LDA(At, 1, 0); PG8_STAGE(PG8_SA(0, 1), a2 + hstepA, voffA);
	s_add_i32 s18, s18, s20
	v_lshl_add_u64 v[168:169], s[14:15], 0, v[142:143]
	s_mov_b32 m0, s18
	ds_read_b128 v[186:189], v173 offset:16384
	ds_read_b128 v[190:193], v173 offset:17408
	ds_read_b128 v[194:197], v173 offset:18432
	ds_read_b128 v[198:201], v173 offset:19456
	ds_read_b128 v[202:205], v173 offset:20480
	ds_read_b128 v[224:227], v173 offset:21504
	ds_read_b128 v[228:231], v173 offset:22528
	ds_read_b128 v[242:245], v173 offset:23552
	global_load_lds_dwordx4 v[168:169], off
	s_add_i32 m0, s18, 0x2000
	v_lshl_add_u64 v[206:207], s[14:15], 0, v[138:139]
	s_add_u32 s14, s14, s48
	s_addc_u32 s15, s15, s49
	s_add_i32 s8, s8, s20
	global_load_lds_dwordx4 v[206:207], off
	v_lshl_add_u64 v[220:221], s[14:15], 0, v[142:143]
	s_mov_b32 m0, s8
	v_lshl_add_u64 v[222:223], s[14:15], 0, v[138:139]
	global_load_lds_dwordx4 v[220:221], off
	s_add_i32 m0, s8, 0x2000
	v_lshl_add_u64 v[232:233], s[10:11], 0, v[144:145]
	global_load_lds_dwordx4 v[222:223], off
	s_mov_b32 m0, s21
	v_lshl_add_u64 v[246:247], s[10:11], 0, v[140:141]
	global_load_lds_dwordx4 v[232:233], off
	s_mov_b32 m0, s22
	s_nop 0
	global_load_lds_dwordx4 v[246:247], off
	s_waitcnt vmcnt(8)
	s_waitcnt lgkmcnt(0)
	s_barrier
	s_waitcnt lgkmcnt(0)
	v_mfma_f32_16x16x32_bf16 v[62:65], v[130:133], v[186:189], v[62:65]
	v_mfma_f32_16x16x32_bf16 v[58:61], v[156:159], v[186:189], v[58:61]
	v_mfma_f32_16x16x32_bf16 v[46:49], v[130:133], v[194:197], v[46:49]
	v_mfma_f32_16x16x32_bf16 v[42:45], v[156:159], v[194:197], v[42:45]
	v_mfma_f32_16x16x32_bf16 v[30:33], v[130:133], v[202:205], v[30:33]
	v_mfma_f32_16x16x32_bf16 v[26:29], v[156:159], v[202:205], v[26:29]
	v_mfma_f32_16x16x32_bf16 v[14:17], v[130:133], v[228:231], v[14:17]
	v_mfma_f32_16x16x32_bf16 v[10:13], v[156:159], v[228:231], v[10:13]
	v_mfma_f32_16x16x32_bf16 v[62:65], v[134:137], v[190:193], v[62:65]
	v_mfma_f32_16x16x32_bf16 v[58:61], v[160:163], v[190:193], v[58:61]
	v_mfma_f32_16x16x32_bf16 v[46:49], v[134:137], v[198:201], v[46:49]
	v_mfma_f32_16x16x32_bf16 v[42:45], v[160:163], v[198:201], v[42:45]
	v_mfma_f32_16x16x32_bf16 v[30:33], v[134:137], v[224:227], v[30:33]
	v_mfma_f32_16x16x32_bf16 v[26:29], v[160:163], v[224:227], v[26:29]
	v_mfma_f32_16x16x32_bf16 v[14:17], v[134:137], v[242:245], v[14:17]
	v_mfma_f32_16x16x32_bf16 v[10:13], v[160:163], v[242:245], v[10:13]
	v_mfma_f32_16x16x32_bf16 v[54:57], v[164:167], v[186:189], v[54:57]
	v_mfma_f32_16x16x32_bf16 v[50:53], v[178:181], v[186:189], v[50:53]
	v_mfma_f32_16x16x32_bf16 v[38:41], v[164:167], v[194:197], v[38:41]
	v_mfma_f32_16x16x32_bf16 v[34:37], v[178:181], v[194:197], v[34:37]
	v_mfma_f32_16x16x32_bf16 v[22:25], v[164:167], v[202:205], v[22:25]
	v_mfma_f32_16x16x32_bf16 v[18:21], v[178:181], v[202:205], v[18:21]
	v_mfma_f32_16x16x32_bf16 v[6:9], v[164:167], v[228:231], v[6:9]
	v_mfma_f32_16x16x32_bf16 v[2:5], v[178:181], v[228:231], v[2:5]
	v_mfma_f32_16x16x32_bf16 v[54:57], v[174:177], v[190:193], v[54:57]
	v_mfma_f32_16x16x32_bf16 v[50:53], v[182:185], v[190:193], v[50:53]
	v_mfma_f32_16x16x32_bf16 v[38:41], v[174:177], v[198:201], v[38:41]
	v_mfma_f32_16x16x32_bf16 v[34:37], v[182:185], v[198:201], v[34:37]
	v_mfma_f32_16x16x32_bf16 v[22:25], v[174:177], v[224:227], v[22:25]
	v_mfma_f32_16x16x32_bf16 v[18:21], v[182:185], v[224:227], v[18:21]
	v_mfma_f32_16x16x32_bf16 v[6:9], v[174:177], v[242:245], v[6:9]
	v_mfma_f32_16x16x32_bf16 v[2:5], v[182:185], v[242:245], v[2:5]
	s_barrier
	s_add_i32 s8, 0, 0x18000
	v_add_u32_e32 v0, s8, v171
	s_add_i32 s14, 0, 0x1c000
	ds_read_b128 v[130:133], v0
	ds_read_b128 v[134:137], v0 offset:1024
	ds_read_b128 v[156:159], v0 offset:2048
	ds_read_b128 v[160:163], v0 offset:3072
	v_add_u32_e32 v0, s14, v171
	ds_read_b128 v[164:167], v0
	ds_read_b128 v[174:177], v0 offset:1024
	ds_read_b128 v[178:181], v0 offset:2048
	ds_read_b128 v[182:185], v0 offset:3072
	s_add_u32 s10, s10, s46
	s_addc_u32 s11, s11, s47
	s_mov_b32 m0, s23
	v_lshl_add_u64 v[248:249], s[10:11], 0, v[144:145]
	ds_read_b128 v[186:189], v173 offset:32768
	ds_read_b128 v[190:193], v173 offset:33792
	ds_read_b128 v[194:197], v173 offset:34816
	ds_read_b128 v[198:201], v173 offset:35840
	ds_read_b128 v[202:205], v173 offset:36864
	ds_read_b128 v[224:227], v173 offset:37888
	ds_read_b128 v[228:231], v173 offset:38912
	ds_read_b128 v[242:245], v173 offset:39936
	global_load_lds_dwordx4 v[248:249], off
	v_lshl_add_u64 v[248:249], s[10:11], 0, v[140:141]
	s_mov_b32 m0, s24
	s_nop 0
	global_load_lds_dwordx4 v[248:249], off
	s_waitcnt vmcnt(8)
	s_waitcnt lgkmcnt(0)
	s_barrier
; #define PG8_STAGE(bufoff, gbase, voff) do { _Pragma("unroll") for (int _i = 0; _i < 2; ++_i) \
;         __builtin_amdgcn_global_load_lds((const unsigned*)((const char*)(gbase) + (voff)[_i]), (LAS unsigned*)(lds + (bufoff) + ldsw + _i * 8192), 16, 0, 0); } while (0)
; #define PG8_LDA(dst, b, h) do { _Pragma("unroll") for (int m = 0; m < 4; ++m) _Pragma("unroll") for (int k = 0; k < 2; ++k) dst[m][k] = *(const LAS bf16x8*)(lds + PG8_SA(b, h) + aoff + m * 2048 + k * 1024); } while (0)
; #define PG8_MMA(ai, bj, At, Bt) do { __builtin_amdgcn_s_setprio(1); _Pragma("unroll") for (int m = 0; m < 4; ++m) _Pragma("unroll") for (int n = 0; n < 2; ++n) _Pragma("unroll") for (int k = 0; k < 2; ++k) \
;         acc[ai][bj][m][n] = __builtin_amdgcn_mfma_f32_16x16x32_bf16(Bt[n][k], At[m][k], acc[ai][bj][m][n], 0, 0, 0); __builtin_amdgcn_s_setprio(0); } while (0)
; #define PG8_WAIT_V(n) asm volatile("s_waitcnt vmcnt(" #n ")" ::: "memory")
; #define PG8_WAIT_L(n) asm volatile("s_waitcnt lgkmcnt(" #n ")" ::: "memory")
; #define PG8_BAR __builtin_amdgcn_s_barrier()
; #define PG8_SCHED __builtin_amdgcn_sched_barrier(0)
; template <class Epi>
; __device__ __forceinline__ void gemm_phase(LAS unsigned char* lds, const Gemm g, const Epi& E) {
;     ...
;             PG8_WAIT_V(8); PG8_WAIT_L(0); PG8_BAR; PG8_MMA(0, 0, At, B0); PG8_MMA(0, 1, At, B1); PG8_BAR; PG8_SCHED;
;             PG8_LDA(At, 1, 1); PG8_STAGE(PG8_SB(1, 0), b3, voffB); PG8_STAGE(PG8_SB(1, 1), b3 + hstepB, voffB); PG8_STAGE(PG8_SA(1, 0), a3, voffA);
;             PG8_WAIT_V(8); PG8_WAIT_L(0); PG8_BAR; PG8_MMA(1, 0, At, B0); PG8_MMA(1, 1, At, B1); PG8_BAR; PG8_SCHED;
;         }
	s_waitcnt lgkmcnt(0)
	v_mfma_f32_16x16x32_bf16 v[122:125], v[130:133], v[186:189], v[122:125]
	v_mfma_f32_16x16x32_bf16 v[126:129], v[156:159], v[186:189], v[126:129]
	v_mfma_f32_16x16x32_bf16 v[110:113], v[130:133], v[194:197], v[110:113]
	v_mfma_f32_16x16x32_bf16 v[106:109], v[156:159], v[194:197], v[106:109]
	v_mfma_f32_16x16x32_bf16 v[94:97], v[130:133], v[202:205], v[94:97]
	v_mfma_f32_16x16x32_bf16 v[90:93], v[156:159], v[202:205], v[90:93]
	v_mfma_f32_16x16x32_bf16 v[78:81], v[130:133], v[228:231], v[78:81]
	v_mfma_f32_16x16x32_bf16 v[74:77], v[156:159], v[228:231], v[74:77]
	v_mfma_f32_16x16x32_bf16 v[122:125], v[134:137], v[190:193], v[122:125]
	v_mfma_f32_16x16x32_bf16 v[126:129], v[160:163], v[190:193], v[126:129]
	v_mfma_f32_16x16x32_bf16 v[110:113], v[134:137], v[198:201], v[110:113]
	v_mfma_f32_16x16x32_bf16 v[106:109], v[160:163], v[198:201], v[106:109]
	v_mfma_f32_16x16x32_bf16 v[94:97], v[134:137], v[224:227], v[94:97]
	v_mfma_f32_16x16x32_bf16 v[90:93], v[160:163], v[224:227], v[90:93]
	v_mfma_f32_16x16x32_bf16 v[78:81], v[134:137], v[242:245], v[78:81]
	v_mfma_f32_16x16x32_bf16 v[74:77], v[160:163], v[242:245], v[74:77]
	v_mfma_f32_16x16x32_bf16 v[118:121], v[164:167], v[186:189], v[118:121]
	v_mfma_f32_16x16x32_bf16 v[114:117], v[178:181], v[186:189], v[114:117]
	v_mfma_f32_16x16x32_bf16 v[102:105], v[164:167], v[194:197], v[102:105]
	v_mfma_f32_16x16x32_bf16 v[98:101], v[178:181], v[194:197], v[98:101]
	v_mfma_f32_16x16x32_bf16 v[86:89], v[164:167], v[202:205], v[86:89]
	v_mfma_f32_16x16x32_bf16 v[82:85], v[178:181], v[202:205], v[82:85]
	v_mfma_f32_16x16x32_bf16 v[70:73], v[164:167], v[228:231], v[70:73]
	v_mfma_f32_16x16x32_bf16 v[66:69], v[178:181], v[228:231], v[66:69]
	v_mfma_f32_16x16x32_bf16 v[118:121], v[174:177], v[190:193], v[118:121]
	v_mfma_f32_16x16x32_bf16 v[114:117], v[182:185], v[190:193], v[114:117]
	v_mfma_f32_16x16x32_bf16 v[102:105], v[174:177], v[198:201], v[102:105]
	v_mfma_f32_16x16x32_bf16 v[98:101], v[182:185], v[198:201], v[98:101]
	v_mfma_f32_16x16x32_bf16 v[86:89], v[174:177], v[224:227], v[86:89]
	v_mfma_f32_16x16x32_bf16 v[82:85], v[182:185], v[224:227], v[82:85]
	v_mfma_f32_16x16x32_bf16 v[70:73], v[174:177], v[242:245], v[70:73]
	v_mfma_f32_16x16x32_bf16 v[66:69], v[182:185], v[242:245], v[66:69]
	s_barrier
	s_add_i32 s8, s8, s20
	v_lshl_add_u64 v[168:169], v[168:169], 0, s[28:29]
	s_mov_b32 m0, s8
	ds_read_b128 v[186:189], v173 offset:49152
	ds_read_b128 v[190:193], v173 offset:50176
	ds_read_b128 v[194:197], v173 offset:51200
	ds_read_b128 v[198:201], v173 offset:52224
	ds_read_b128 v[202:205], v173 offset:53248
	ds_read_b128 v[224:227], v173 offset:54272
	ds_read_b128 v[228:231], v173 offset:55296
	ds_read_b128 v[242:245], v173 offset:56320
	global_load_lds_dwordx4 v[168:169], off
	v_lshl_add_u64 v[168:169], v[206:207], 0, s[28:29]
	s_add_i32 m0, s8, 0x2000
	s_add_i32 s8, s14, s20
	global_load_lds_dwordx4 v[168:169], off
	v_lshl_add_u64 v[168:169], v[220:221], 0, s[28:29]
	s_mov_b32 m0, s8
	s_nop 0
	global_load_lds_dwordx4 v[168:169], off
	v_lshl_add_u64 v[168:169], v[222:223], 0, s[28:29]
	s_add_i32 m0, s8, 0x2000
	s_nop 0
	global_load_lds_dwordx4 v[168:169], off
	v_lshl_add_u64 v[168:169], v[232:233], 0, s[28:29]
	s_mov_b32 m0, s25
	s_nop 0
	global_load_lds_dwordx4 v[168:169], off
	v_lshl_add_u64 v[168:169], v[246:247], 0, s[28:29]
	s_mov_b32 m0, s58
	s_nop 0
	global_load_lds_dwordx4 v[168:169], off
	s_waitcnt vmcnt(8)
	s_waitcnt lgkmcnt(0)
	s_barrier
	s_waitcnt lgkmcnt(0)
	v_mfma_f32_16x16x32_bf16 v[62:65], v[130:133], v[186:189], v[62:65]
	v_mfma_f32_16x16x32_bf16 v[58:61], v[156:159], v[186:189], v[58:61]
	v_mfma_f32_16x16x32_bf16 v[46:49], v[130:133], v[194:197], v[46:49]
	v_mfma_f32_16x16x32_bf16 v[42:45], v[156:159], v[194:197], v[42:45]
	v_mfma_f32_16x16x32_bf16 v[30:33], v[130:133], v[202:205], v[30:33]
	v_mfma_f32_16x16x32_bf16 v[26:29], v[156:159], v[202:205], v[26:29]
	v_mfma_f32_16x16x32_bf16 v[14:17], v[130:133], v[228:231], v[14:17]
	v_mfma_f32_16x16x32_bf16 v[10:13], v[156:159], v[228:231], v[10:13]
	v_mfma_f32_16x16x32_bf16 v[62:65], v[134:137], v[190:193], v[62:65]
	v_mfma_f32_16x16x32_bf16 v[58:61], v[160:163], v[190:193], v[58:61]
	v_mfma_f32_16x16x32_bf16 v[46:49], v[134:137], v[198:201], v[46:49]
	v_mfma_f32_16x16x32_bf16 v[42:45], v[160:163], v[198:201], v[42:45]
	v_mfma_f32_16x16x32_bf16 v[30:33], v[134:137], v[224:227], v[30:33]
	v_mfma_f32_16x16x32_bf16 v[26:29], v[160:163], v[224:227], v[26:29]
	v_mfma_f32_16x16x32_bf16 v[14:17], v[134:137], v[242:245], v[14:17]
	v_mfma_f32_16x16x32_bf16 v[10:13], v[160:163], v[242:245], v[10:13]
	v_mfma_f32_16x16x32_bf16 v[54:57], v[164:167], v[186:189], v[54:57]
	v_mfma_f32_16x16x32_bf16 v[50:53], v[178:181], v[186:189], v[50:53]
	v_mfma_f32_16x16x32_bf16 v[38:41], v[164:167], v[194:197], v[38:41]
	v_mfma_f32_16x16x32_bf16 v[34:37], v[178:181], v[194:197], v[34:37]
	v_mfma_f32_16x16x32_bf16 v[22:25], v[164:167], v[202:205], v[22:25]
	v_mfma_f32_16x16x32_bf16 v[18:21], v[178:181], v[202:205], v[18:21]
	v_mfma_f32_16x16x32_bf16 v[6:9], v[164:167], v[228:231], v[6:9]
	v_mfma_f32_16x16x32_bf16 v[2:5], v[178:181], v[228:231], v[2:5]
	v_mfma_f32_16x16x32_bf16 v[54:57], v[174:177], v[190:193], v[54:57]
	v_mfma_f32_16x16x32_bf16 v[50:53], v[182:185], v[190:193], v[50:53]
	v_mfma_f32_16x16x32_bf16 v[38:41], v[174:177], v[198:201], v[38:41]
	v_mfma_f32_16x16x32_bf16 v[34:37], v[182:185], v[198:201], v[34:37]
	v_mfma_f32_16x16x32_bf16 v[22:25], v[174:177], v[224:227], v[22:25]
	v_mfma_f32_16x16x32_bf16 v[18:21], v[182:185], v[224:227], v[18:21]
	v_mfma_f32_16x16x32_bf16 v[6:9], v[174:177], v[242:245], v[6:9]
	v_mfma_f32_16x16x32_bf16 v[2:5], v[182:185], v[242:245], v[2:5]
	s_barrier
	s_add_u32 s0, s0, 0x100
	s_addc_u32 s1, s1, 0
	s_add_u32 s6, s6, 0x100
	s_addc_u32 s7, s7, 0
	s_cmp_ge_i32 s9, s61
	s_mov_b32 s8, s9
	s_cbranch_scc0 .LBB0_328
	s_setprio 0

; #define PG8_STAGE(bufoff, gbase, voff) do { _Pragma("unroll") for (int _i = 0; _i < 2; ++_i) \
;         __builtin_amdgcn_global_load_lds((const unsigned*)((const char*)(gbase) + (voff)[_i]), (LAS unsigned*)(lds + (bufoff) + ldsw + _i * 8192), 16, 0, 0); } while (0)
; #define PG8_LDA(dst, b, h) do { _Pragma("unroll") for (int m = 0; m < 4; ++m) _Pragma("unroll") for (int k = 0; k < 2; ++k) dst[m][k] = *(const LAS bf16x8*)(lds + PG8_SA(b, h) + aoff + m * 2048 + k * 1024); } while (0)
; #define PG8_LDB(dst, b, h) do { _Pragma("unroll") for (int n = 0; n < 2; ++n) _Pragma("unroll") for (int k = 0; k < 2; ++k) dst[n][k] = *(const LAS bf16x8*)(lds + PG8_SB(b, h) + boff + n * 2048 + k * 1024); } while (0)
; #define PG8_MMA(ai, bj, At, Bt) do { __builtin_amdgcn_s_setprio(1); _Pragma("unroll") for (int m = 0; m < 4; ++m) _Pragma("unroll") for (int n = 0; n < 2; ++n) _Pragma("unroll") for (int k = 0; k < 2; ++k) \
;         acc[ai][bj][m][n] = __builtin_amdgcn_mfma_f32_16x16x32_bf16(Bt[n][k], At[m][k], acc[ai][bj][m][n], 0, 0, 0); __builtin_amdgcn_s_setprio(0); } while (0)
; #define PG8_WAIT_V(n) asm volatile("s_waitcnt vmcnt(" #n ")" ::: "memory")
; #define PG8_WAIT_L(n) asm volatile("s_waitcnt lgkmcnt(" #n ")" ::: "memory")
; #define PG8_BAR __builtin_amdgcn_s_barrier()
; #define PG8_SCHED __builtin_amdgcn_sched_barrier(0)
; template <class Epi>
; __device__ __forceinline__ void gemm_phase(LAS unsigned char* lds, const Gemm g, const Epi& E) {
;     ...
;             const bool last = (t == nt - 2);
;             const char* a1 = cA + (size_t)(t + 1) * kstep;
;             const char* a2 = last ? nA : cA + (size_t)(t + 2) * kstep; const char* b2 = last ? nB : cB + (size_t)(t + 2) * kstep;
;             const char* a3 = a2 + kstep; const char* b3 = b2 + kstep;
;             PG8_LDB(B0, 0, 0); PG8_LDB(B1, 0, 1); PG8_SCHED; PG8_LDA(At, 0, 0); PG8_STAGE(PG8_SA(1, 1), a1 + hstepA, voffA);
;             PG8_WAIT_V(8); PG8_WAIT_L(0); PG8_BAR; PG8_MMA(0, 0, At, B0); PG8_MMA(0, 1, At, B1); PG8_BAR; PG8_SCHED;
;     ...
; #pragma unroll
;         for (int a = 0; a < 2; ++a)
; #pragma unroll
;             for (int b = 0; b < 2; ++b)
; #pragma unroll
;                 for (int m = 0; m < 4; ++m)
; #pragma unroll
;                     for (int n = 0; n < 2; ++n) acc[a][b][m][n] = (f32x4){0.f, 0.f, 0.f, 0.f};
;         cur = nxt; cA = nA; cB = nB; ++ui;
.Lukv_ssq_skip:
	s_add_u32 s48, s48, 0x80
	s_addc_u32 s49, s49, 0
	s_add_u32 s20, s50, 0x100
	s_addc_u32 s21, s51, 0
	s_mov_b32 s50, 0
	v_mov_b64_e32 v[2:3], 0
	v_mov_b64_e32 v[4:5], 0
	v_mov_b64_e32 v[6:7], 0
	v_mov_b64_e32 v[8:9], 0
	v_mov_b64_e32 v[10:11], 0
	v_mov_b64_e32 v[12:13], 0
	v_mov_b64_e32 v[14:15], 0
	v_mov_b64_e32 v[16:17], 0
	v_mov_b64_e32 v[18:19], 0
	v_mov_b64_e32 v[20:21], 0
	v_mov_b64_e32 v[22:23], 0
	v_mov_b64_e32 v[24:25], 0
	v_mov_b64_e32 v[26:27], 0
	v_mov_b64_e32 v[28:29], 0
	v_mov_b64_e32 v[30:31], 0
	v_mov_b64_e32 v[32:33], 0
	v_mov_b64_e32 v[34:35], 0
	v_mov_b64_e32 v[36:37], 0
	v_mov_b64_e32 v[38:39], 0
	v_mov_b64_e32 v[40:41], 0
	v_mov_b64_e32 v[42:43], 0
	v_mov_b64_e32 v[44:45], 0
	v_mov_b64_e32 v[46:47], 0
	v_mov_b64_e32 v[48:49], 0
	v_mov_b64_e32 v[50:51], 0
	v_mov_b64_e32 v[52:53], 0
	v_mov_b64_e32 v[54:55], 0
	v_mov_b64_e32 v[56:57], 0
	v_mov_b64_e32 v[58:59], 0
	v_mov_b64_e32 v[60:61], 0
	v_mov_b64_e32 v[62:63], 0
	v_mov_b64_e32 v[64:65], 0
	v_mov_b64_e32 v[66:67], 0
	v_mov_b64_e32 v[68:69], 0
	v_mov_b64_e32 v[70:71], 0
	v_mov_b64_e32 v[72:73], 0
	v_mov_b64_e32 v[74:75], 0
	v_mov_b64_e32 v[76:77], 0
	v_mov_b64_e32 v[78:79], 0
	v_mov_b64_e32 v[80:81], 0
	v_mov_b64_e32 v[82:83], 0
	v_mov_b64_e32 v[84:85], 0
	v_mov_b64_e32 v[86:87], 0
	v_mov_b64_e32 v[88:89], 0
	v_mov_b64_e32 v[90:91], 0
	v_mov_b64_e32 v[92:93], 0
	v_mov_b64_e32 v[94:95], 0
	v_mov_b64_e32 v[96:97], 0
	v_mov_b64_e32 v[98:99], 0
	v_mov_b64_e32 v[100:101], 0
	v_mov_b64_e32 v[102:103], 0
	v_mov_b64_e32 v[104:105], 0
	v_mov_b64_e32 v[106:107], 0
	v_mov_b64_e32 v[108:109], 0
	v_mov_b64_e32 v[110:111], 0
	v_mov_b64_e32 v[112:113], 0
	v_mov_b64_e32 v[114:115], 0
	v_mov_b64_e32 v[116:117], 0
	v_mov_b64_e32 v[118:119], 0
	v_mov_b64_e32 v[120:121], 0
	v_mov_b64_e32 v[122:123], 0
	v_mov_b64_e32 v[124:125], 0
	v_mov_b64_e32 v[126:127], 0
	v_mov_b64_e32 v[128:129], 0
	s_and_b64 vcc, exec, s[44:45]
	s_cbranch_vccnz .Lg385_prio_skip
	s_setprio 1
.Lg385_prio_skip:
.LBB0_385:
	s_add_i32 s59, s50, 2
	s_add_u32 s61, s48, 0x80
	s_addc_u32 s51, s49, 0
	s_add_i32 s70, 0, 0x10000
	s_cmp_eq_u32 s35, s50
	s_cselect_b32 s51, s43, s51
	s_cselect_b32 s50, s42, s61
	v_add_u32_e32 v144, s70, v147
	s_cselect_b32 s63, s47, s21
	s_cselect_b32 s62, s46, s20
	s_add_i32 s61, 0, 0x14000
	ds_read_b128 v[140:143], v144
	ds_read_b128 v[150:153], v144 offset:1024
	ds_read_b128 v[154:157], v144 offset:2048
	ds_read_b128 v[158:161], v144 offset:3072
	v_add_u32_e32 v144, s61, v147
	ds_read_b128 v[162:165], v144
	ds_read_b128 v[166:169], v144 offset:1024
	ds_read_b128 v[170:173], v144 offset:2048
	ds_read_b128 v[174:177], v144 offset:3072
	v_lshl_add_u64 v[144:145], s[48:49], 0, v[136:137]
	s_add_i32 m0, s7, 0xc000
	ds_read_b128 v[178:181], v149
	ds_read_b128 v[182:185], v149 offset:1024
	ds_read_b128 v[186:189], v149 offset:2048
	ds_read_b128 v[190:193], v149 offset:3072
	ds_read_b128 v[194:197], v149 offset:4096
	ds_read_b128 v[198:201], v149 offset:5120
	ds_read_b128 v[202:205], v149 offset:6144
	ds_read_b128 v[224:227], v149 offset:7168
	global_load_lds_dwordx4 v[144:145], off
	v_lshl_add_u64 v[144:145], s[48:49], 0, v[138:139]
	s_add_i32 m0, s7, 0xe000
	s_nop 0
	global_load_lds_dwordx4 v[144:145], off
	s_waitcnt vmcnt(8)
	s_waitcnt lgkmcnt(0)
	s_barrier
	s_waitcnt lgkmcnt(0)
	v_mfma_f32_16x16x32_bf16 v[122:125], v[140:143], v[178:181], v[122:125]
	v_mfma_f32_16x16x32_bf16 v[126:129], v[154:157], v[178:181], v[126:129]
	v_mfma_f32_16x16x32_bf16 v[110:113], v[140:143], v[186:189], v[110:113]
	v_mfma_f32_16x16x32_bf16 v[106:109], v[154:157], v[186:189], v[106:109]
	v_mfma_f32_16x16x32_bf16 v[94:97], v[140:143], v[194:197], v[94:97]
	v_mfma_f32_16x16x32_bf16 v[90:93], v[154:157], v[194:197], v[90:93]
	v_mfma_f32_16x16x32_bf16 v[78:81], v[140:143], v[202:205], v[78:81]
	v_mfma_f32_16x16x32_bf16 v[74:77], v[154:157], v[202:205], v[74:77]
	v_mfma_f32_16x16x32_bf16 v[122:125], v[150:153], v[182:185], v[122:125]
	v_mfma_f32_16x16x32_bf16 v[126:129], v[158:161], v[182:185], v[126:129]
	v_mfma_f32_16x16x32_bf16 v[110:113], v[150:153], v[190:193], v[110:113]
	v_mfma_f32_16x16x32_bf16 v[106:109], v[158:161], v[190:193], v[106:109]
	v_mfma_f32_16x16x32_bf16 v[94:97], v[150:153], v[198:201], v[94:97]
	v_mfma_f32_16x16x32_bf16 v[90:93], v[158:161], v[198:201], v[90:93]
	v_mfma_f32_16x16x32_bf16 v[78:81], v[150:153], v[224:227], v[78:81]
	v_mfma_f32_16x16x32_bf16 v[74:77], v[158:161], v[224:227], v[74:77]
	v_mfma_f32_16x16x32_bf16 v[118:121], v[162:165], v[178:181], v[118:121]
	v_mfma_f32_16x16x32_bf16 v[114:117], v[170:173], v[178:181], v[114:117]
	v_mfma_f32_16x16x32_bf16 v[102:105], v[162:165], v[186:189], v[102:105]
	v_mfma_f32_16x16x32_bf16 v[98:101], v[170:173], v[186:189], v[98:101]
	v_mfma_f32_16x16x32_bf16 v[86:89], v[162:165], v[194:197], v[86:89]
	v_mfma_f32_16x16x32_bf16 v[82:85], v[170:173], v[194:197], v[82:85]
	v_mfma_f32_16x16x32_bf16 v[70:73], v[162:165], v[202:205], v[70:73]
	v_mfma_f32_16x16x32_bf16 v[66:69], v[170:173], v[202:205], v[66:69]
	v_mfma_f32_16x16x32_bf16 v[118:121], v[166:169], v[182:185], v[118:121]
	v_mfma_f32_16x16x32_bf16 v[114:117], v[174:177], v[182:185], v[114:117]
	v_mfma_f32_16x16x32_bf16 v[102:105], v[166:169], v[190:193], v[102:105]
	v_mfma_f32_16x16x32_bf16 v[98:101], v[174:177], v[190:193], v[98:101]
	v_mfma_f32_16x16x32_bf16 v[86:89], v[166:169], v[198:201], v[86:89]
	v_mfma_f32_16x16x32_bf16 v[82:85], v[174:177], v[198:201], v[82:85]
	v_mfma_f32_16x16x32_bf16 v[70:73], v[166:169], v[224:227], v[70:73]
	v_mfma_f32_16x16x32_bf16 v[66:69], v[174:177], v[224:227], v[66:69]
	s_barrier
; #define PG8_STAGE(bufoff, gbase, voff) do { _Pragma("unroll") for (int _i = 0; _i < 2; ++_i) \
;         __builtin_amdgcn_global_load_lds((const unsigned*)((const char*)(gbase) + (voff)[_i]), (LAS unsigned*)(lds + (bufoff) + ldsw + _i * 8192), 16, 0, 0); } while (0)
; #define PG8_LDA(dst, b, h) do { _Pragma("unroll") for (int m = 0; m < 4; ++m) _Pragma("unroll") for (int k = 0; k < 2; ++k) dst[m][k] = *(const LAS bf16x8*)(lds + PG8_SA(b, h) + aoff + m * 2048 + k * 1024); } while (0)
; #define PG8_LDB(dst, b, h) do { _Pragma("unroll") for (int n = 0; n < 2; ++n) _Pragma("unroll") for (int k = 0; k < 2; ++k) dst[n][k] = *(const LAS bf16x8*)(lds + PG8_SB(b, h) + boff + n * 2048 + k * 1024); } while (0)
; #define PG8_MMA(ai, bj, At, Bt) do { __builtin_amdgcn_s_setprio(1); _Pragma("unroll") for (int m = 0; m < 4; ++m) _Pragma("unroll") for (int n = 0; n < 2; ++n) _Pragma("unroll") for (int k = 0; k < 2; ++k) \
;         acc[ai][bj][m][n] = __builtin_amdgcn_mfma_f32_16x16x32_bf16(Bt[n][k], At[m][k], acc[ai][bj][m][n], 0, 0, 0); __builtin_amdgcn_s_setprio(0); } while (0)
; #define PG8_WAIT_V(n) asm volatile("s_waitcnt vmcnt(" #n ")" ::: "memory")
; #define PG8_WAIT_L(n) asm volatile("s_waitcnt lgkmcnt(" #n ")" ::: "memory")
; #define PG8_BAR __builtin_amdgcn_s_barrier()
; #define PG8_SCHED __builtin_amdgcn_sched_barrier(0)
; template <class Epi>
; __device__ __forceinline__ void gemm_phase(LAS unsigned char* lds, const Gemm g, const Epi& E) {
;     ...
;             PG8_LDA(At, 0, 1); PG8_STAGE(PG8_SB(0, 0), b2, voffB); PG8_STAGE(PG8_SB(0, 1), b2 + hstepB, voffB); PG8_STAGE(PG8_SA(0, 0), a2, voffA);
;             PG8_WAIT_V(8); PG8_WAIT_L(0); PG8_BAR; PG8_MMA(1, 0, At, B0); PG8_MMA(1, 1, At, B1); PG8_BAR; PG8_SCHED;
;             PG8_LDB(B0, 1, 0); PG8_LDB(B1, 1, 1); PG8_SCHED; PG8_LDA(At, 1, 0); PG8_STAGE(PG8_SA(0, 1), a2 + hstepA, voffA);
	s_add_i32 s70, s70, s6
	v_lshl_add_u64 v[144:145], s[62:63], 0, v[0:1]
	s_mov_b32 m0, s70
	ds_read_b128 v[178:181], v149 offset:16384
	ds_read_b128 v[182:185], v149 offset:17408
	ds_read_b128 v[186:189], v149 offset:18432
	ds_read_b128 v[190:193], v149 offset:19456
	ds_read_b128 v[194:197], v149 offset:20480
	ds_read_b128 v[198:201], v149 offset:21504
	ds_read_b128 v[202:205], v149 offset:22528
	ds_read_b128 v[224:227], v149 offset:23552
	global_load_lds_dwordx4 v[144:145], off
	s_add_i32 m0, s70, 0x2000
	v_lshl_add_u64 v[206:207], s[62:63], 0, v[130:131]
	s_add_u32 s62, s62, s10
	s_addc_u32 s63, s63, s11
	s_add_i32 s61, s61, s6
	global_load_lds_dwordx4 v[206:207], off
	v_lshl_add_u64 v[220:221], s[62:63], 0, v[0:1]
	s_mov_b32 m0, s61
	v_lshl_add_u64 v[222:223], s[62:63], 0, v[130:131]
	global_load_lds_dwordx4 v[220:221], off
	s_add_i32 m0, s61, 0x2000
	v_lshl_add_u64 v[228:229], s[50:51], 0, v[134:135]
	global_load_lds_dwordx4 v[222:223], off
	s_mov_b32 m0, s7
	v_lshl_add_u64 v[230:231], s[50:51], 0, v[132:133]
	global_load_lds_dwordx4 v[228:229], off
	s_mov_b32 m0, s8
	s_nop 0
	global_load_lds_dwordx4 v[230:231], off
	s_waitcnt vmcnt(8)
	s_waitcnt lgkmcnt(0)
	s_barrier
	s_waitcnt lgkmcnt(0)
	v_mfma_f32_16x16x32_bf16 v[62:65], v[140:143], v[178:181], v[62:65]
	v_mfma_f32_16x16x32_bf16 v[58:61], v[154:157], v[178:181], v[58:61]
	v_mfma_f32_16x16x32_bf16 v[46:49], v[140:143], v[186:189], v[46:49]
	v_mfma_f32_16x16x32_bf16 v[42:45], v[154:157], v[186:189], v[42:45]
	v_mfma_f32_16x16x32_bf16 v[30:33], v[140:143], v[194:197], v[30:33]
	v_mfma_f32_16x16x32_bf16 v[26:29], v[154:157], v[194:197], v[26:29]
	v_mfma_f32_16x16x32_bf16 v[14:17], v[140:143], v[202:205], v[14:17]
	v_mfma_f32_16x16x32_bf16 v[10:13], v[154:157], v[202:205], v[10:13]
	v_mfma_f32_16x16x32_bf16 v[62:65], v[150:153], v[182:185], v[62:65]
	v_mfma_f32_16x16x32_bf16 v[58:61], v[158:161], v[182:185], v[58:61]
	v_mfma_f32_16x16x32_bf16 v[46:49], v[150:153], v[190:193], v[46:49]
	v_mfma_f32_16x16x32_bf16 v[42:45], v[158:161], v[190:193], v[42:45]
	v_mfma_f32_16x16x32_bf16 v[30:33], v[150:153], v[198:201], v[30:33]
	v_mfma_f32_16x16x32_bf16 v[26:29], v[158:161], v[198:201], v[26:29]
	v_mfma_f32_16x16x32_bf16 v[14:17], v[150:153], v[224:227], v[14:17]
	v_mfma_f32_16x16x32_bf16 v[10:13], v[158:161], v[224:227], v[10:13]
	v_mfma_f32_16x16x32_bf16 v[54:57], v[162:165], v[178:181], v[54:57]
	v_mfma_f32_16x16x32_bf16 v[50:53], v[170:173], v[178:181], v[50:53]
	v_mfma_f32_16x16x32_bf16 v[38:41], v[162:165], v[186:189], v[38:41]
	v_mfma_f32_16x16x32_bf16 v[34:37], v[170:173], v[186:189], v[34:37]
	v_mfma_f32_16x16x32_bf16 v[22:25], v[162:165], v[194:197], v[22:25]
	v_mfma_f32_16x16x32_bf16 v[18:21], v[170:173], v[194:197], v[18:21]
	v_mfma_f32_16x16x32_bf16 v[6:9], v[162:165], v[202:205], v[6:9]
	v_mfma_f32_16x16x32_bf16 v[2:5], v[170:173], v[202:205], v[2:5]
	v_mfma_f32_16x16x32_bf16 v[54:57], v[166:169], v[182:185], v[54:57]
	v_mfma_f32_16x16x32_bf16 v[50:53], v[174:177], v[182:185], v[50:53]
	v_mfma_f32_16x16x32_bf16 v[38:41], v[166:169], v[190:193], v[38:41]
	v_mfma_f32_16x16x32_bf16 v[34:37], v[174:177], v[190:193], v[34:37]
	v_mfma_f32_16x16x32_bf16 v[22:25], v[166:169], v[198:201], v[22:25]
	v_mfma_f32_16x16x32_bf16 v[18:21], v[174:177], v[198:201], v[18:21]
	v_mfma_f32_16x16x32_bf16 v[6:9], v[166:169], v[224:227], v[6:9]
	v_mfma_f32_16x16x32_bf16 v[2:5], v[174:177], v[224:227], v[2:5]
	s_barrier
	s_add_i32 s61, 0, 0x18000
	s_add_i32 s62, 0, 0x1c000
	v_add_u32_e32 v158, s61, v147
	v_add_u32_e32 v174, s62, v147
	ds_read_b128 v[140:143], v158
	ds_read_b128 v[150:153], v158 offset:1024
	ds_read_b128 v[154:157], v158 offset:2048
	ds_read_b128 v[158:161], v158 offset:3072
	ds_read_b128 v[162:165], v174
	ds_read_b128 v[166:169], v174 offset:1024
	ds_read_b128 v[170:173], v174 offset:2048
	ds_read_b128 v[174:177], v174 offset:3072
	s_add_u32 s50, s50, s0
	s_addc_u32 s51, s51, s1
	s_mov_b32 m0, s9
	v_lshl_add_u64 v[232:233], s[50:51], 0, v[134:135]
	ds_read_b128 v[178:181], v149 offset:32768
	ds_read_b128 v[182:185], v149 offset:33792
	ds_read_b128 v[186:189], v149 offset:34816
	ds_read_b128 v[190:193], v149 offset:35840
	ds_read_b128 v[194:197], v149 offset:36864
	ds_read_b128 v[198:201], v149 offset:37888
	ds_read_b128 v[202:205], v149 offset:38912
	ds_read_b128 v[224:227], v149 offset:39936
	global_load_lds_dwordx4 v[232:233], off
	v_lshl_add_u64 v[232:233], s[50:51], 0, v[132:133]
	s_mov_b32 m0, s18
	s_nop 0
	global_load_lds_dwordx4 v[232:233], off
	s_waitcnt vmcnt(8)
	s_waitcnt lgkmcnt(0)
	s_barrier
; #define PG8_STAGE(bufoff, gbase, voff) do { _Pragma("unroll") for (int _i = 0; _i < 2; ++_i) \
;         __builtin_amdgcn_global_load_lds((const unsigned*)((const char*)(gbase) + (voff)[_i]), (LAS unsigned*)(lds + (bufoff) + ldsw + _i * 8192), 16, 0, 0); } while (0)
; #define PG8_LDA(dst, b, h) do { _Pragma("unroll") for (int m = 0; m < 4; ++m) _Pragma("unroll") for (int k = 0; k < 2; ++k) dst[m][k] = *(const LAS bf16x8*)(lds + PG8_SA(b, h) + aoff + m * 2048 + k * 1024); } while (0)
; #define PG8_MMA(ai, bj, At, Bt) do { __builtin_amdgcn_s_setprio(1); _Pragma("unroll") for (int m = 0; m < 4; ++m) _Pragma("unroll") for (int n = 0; n < 2; ++n) _Pragma("unroll") for (int k = 0; k < 2; ++k) \
;         acc[ai][bj][m][n] = __builtin_amdgcn_mfma_f32_16x16x32_bf16(Bt[n][k], At[m][k], acc[ai][bj][m][n], 0, 0, 0); __builtin_amdgcn_s_setprio(0); } while (0)
; #define PG8_WAIT_V(n) asm volatile("s_waitcnt vmcnt(" #n ")" ::: "memory")
; #define PG8_WAIT_L(n) asm volatile("s_waitcnt lgkmcnt(" #n ")" ::: "memory")
; #define PG8_BAR __builtin_amdgcn_s_barrier()
; #define PG8_SCHED __builtin_amdgcn_sched_barrier(0)
; template <class Epi>
; __device__ __forceinline__ void gemm_phase(LAS unsigned char* lds, const Gemm g, const Epi& E) {
;     ...
;             PG8_WAIT_V(8); PG8_WAIT_L(0); PG8_BAR; PG8_MMA(0, 0, At, B0); PG8_MMA(0, 1, At, B1); PG8_BAR; PG8_SCHED;
;             PG8_LDA(At, 1, 1); PG8_STAGE(PG8_SB(1, 0), b3, voffB); PG8_STAGE(PG8_SB(1, 1), b3 + hstepB, voffB); PG8_STAGE(PG8_SA(1, 0), a3, voffA);
;             PG8_WAIT_V(8); PG8_WAIT_L(0); PG8_BAR; PG8_MMA(1, 0, At, B0); PG8_MMA(1, 1, At, B1); PG8_BAR; PG8_SCHED;
;         }
	s_waitcnt lgkmcnt(0)
	v_mfma_f32_16x16x32_bf16 v[122:125], v[140:143], v[178:181], v[122:125]
	v_mfma_f32_16x16x32_bf16 v[126:129], v[154:157], v[178:181], v[126:129]
	v_mfma_f32_16x16x32_bf16 v[110:113], v[140:143], v[186:189], v[110:113]
	v_mfma_f32_16x16x32_bf16 v[106:109], v[154:157], v[186:189], v[106:109]
	v_mfma_f32_16x16x32_bf16 v[94:97], v[140:143], v[194:197], v[94:97]
	v_mfma_f32_16x16x32_bf16 v[90:93], v[154:157], v[194:197], v[90:93]
	v_mfma_f32_16x16x32_bf16 v[78:81], v[140:143], v[202:205], v[78:81]
	v_mfma_f32_16x16x32_bf16 v[74:77], v[154:157], v[202:205], v[74:77]
	v_mfma_f32_16x16x32_bf16 v[122:125], v[150:153], v[182:185], v[122:125]
	v_mfma_f32_16x16x32_bf16 v[126:129], v[158:161], v[182:185], v[126:129]
	v_mfma_f32_16x16x32_bf16 v[110:113], v[150:153], v[190:193], v[110:113]
	v_mfma_f32_16x16x32_bf16 v[106:109], v[158:161], v[190:193], v[106:109]
	v_mfma_f32_16x16x32_bf16 v[94:97], v[150:153], v[198:201], v[94:97]
	v_mfma_f32_16x16x32_bf16 v[90:93], v[158:161], v[198:201], v[90:93]
	v_mfma_f32_16x16x32_bf16 v[78:81], v[150:153], v[224:227], v[78:81]
	v_mfma_f32_16x16x32_bf16 v[74:77], v[158:161], v[224:227], v[74:77]
	v_mfma_f32_16x16x32_bf16 v[118:121], v[162:165], v[178:181], v[118:121]
	v_mfma_f32_16x16x32_bf16 v[114:117], v[170:173], v[178:181], v[114:117]
	v_mfma_f32_16x16x32_bf16 v[102:105], v[162:165], v[186:189], v[102:105]
	v_mfma_f32_16x16x32_bf16 v[98:101], v[170:173], v[186:189], v[98:101]
	v_mfma_f32_16x16x32_bf16 v[86:89], v[162:165], v[194:197], v[86:89]
	v_mfma_f32_16x16x32_bf16 v[82:85], v[170:173], v[194:197], v[82:85]
	v_mfma_f32_16x16x32_bf16 v[70:73], v[162:165], v[202:205], v[70:73]
	v_mfma_f32_16x16x32_bf16 v[66:69], v[170:173], v[202:205], v[66:69]
	v_mfma_f32_16x16x32_bf16 v[118:121], v[166:169], v[182:185], v[118:121]
	v_mfma_f32_16x16x32_bf16 v[114:117], v[174:177], v[182:185], v[114:117]
	v_mfma_f32_16x16x32_bf16 v[102:105], v[166:169], v[190:193], v[102:105]
	v_mfma_f32_16x16x32_bf16 v[98:101], v[174:177], v[190:193], v[98:101]
	v_mfma_f32_16x16x32_bf16 v[86:89], v[166:169], v[198:201], v[86:89]
	v_mfma_f32_16x16x32_bf16 v[82:85], v[174:177], v[198:201], v[82:85]
	v_mfma_f32_16x16x32_bf16 v[70:73], v[166:169], v[224:227], v[70:73]
	v_mfma_f32_16x16x32_bf16 v[66:69], v[174:177], v[224:227], v[66:69]
	s_barrier
	s_add_i32 s50, s61, s6
	v_lshl_add_u64 v[144:145], v[144:145], 0, s[28:29]
	s_mov_b32 m0, s50
	ds_read_b128 v[178:181], v149 offset:49152
	ds_read_b128 v[182:185], v149 offset:50176
	ds_read_b128 v[186:189], v149 offset:51200
	ds_read_b128 v[190:193], v149 offset:52224
	ds_read_b128 v[194:197], v149 offset:53248
	ds_read_b128 v[198:201], v149 offset:54272
	ds_read_b128 v[202:205], v149 offset:55296
	ds_read_b128 v[224:227], v149 offset:56320
	global_load_lds_dwordx4 v[144:145], off
	v_lshl_add_u64 v[144:145], v[206:207], 0, s[28:29]
	s_add_i32 m0, s50, 0x2000
	s_add_i32 s50, s62, s6
	global_load_lds_dwordx4 v[144:145], off
	v_lshl_add_u64 v[144:145], v[220:221], 0, s[28:29]
	s_mov_b32 m0, s50
	s_nop 0
	global_load_lds_dwordx4 v[144:145], off
	v_lshl_add_u64 v[144:145], v[222:223], 0, s[28:29]
	s_add_i32 m0, s50, 0x2000
	s_nop 0
	global_load_lds_dwordx4 v[144:145], off
	v_lshl_add_u64 v[144:145], v[228:229], 0, s[28:29]
	s_mov_b32 m0, s24
	s_nop 0
	global_load_lds_dwordx4 v[144:145], off
	v_lshl_add_u64 v[144:145], v[230:231], 0, s[28:29]
	s_mov_b32 m0, s25
	s_nop 0
	global_load_lds_dwordx4 v[144:145], off
	s_waitcnt vmcnt(8)
	s_waitcnt lgkmcnt(0)
	s_barrier
	s_waitcnt lgkmcnt(0)
	v_mfma_f32_16x16x32_bf16 v[62:65], v[140:143], v[178:181], v[62:65]
	v_mfma_f32_16x16x32_bf16 v[58:61], v[154:157], v[178:181], v[58:61]
	v_mfma_f32_16x16x32_bf16 v[46:49], v[140:143], v[186:189], v[46:49]
	v_mfma_f32_16x16x32_bf16 v[42:45], v[154:157], v[186:189], v[42:45]
	v_mfma_f32_16x16x32_bf16 v[30:33], v[140:143], v[194:197], v[30:33]
	v_mfma_f32_16x16x32_bf16 v[26:29], v[154:157], v[194:197], v[26:29]
	v_mfma_f32_16x16x32_bf16 v[14:17], v[140:143], v[202:205], v[14:17]
	v_mfma_f32_16x16x32_bf16 v[10:13], v[154:157], v[202:205], v[10:13]
	v_mfma_f32_16x16x32_bf16 v[62:65], v[150:153], v[182:185], v[62:65]
	v_mfma_f32_16x16x32_bf16 v[58:61], v[158:161], v[182:185], v[58:61]
	v_mfma_f32_16x16x32_bf16 v[46:49], v[150:153], v[190:193], v[46:49]
	v_mfma_f32_16x16x32_bf16 v[42:45], v[158:161], v[190:193], v[42:45]
	v_mfma_f32_16x16x32_bf16 v[30:33], v[150:153], v[198:201], v[30:33]
	v_mfma_f32_16x16x32_bf16 v[26:29], v[158:161], v[198:201], v[26:29]
	v_mfma_f32_16x16x32_bf16 v[14:17], v[150:153], v[224:227], v[14:17]
	v_mfma_f32_16x16x32_bf16 v[10:13], v[158:161], v[224:227], v[10:13]
	v_mfma_f32_16x16x32_bf16 v[54:57], v[162:165], v[178:181], v[54:57]
	v_mfma_f32_16x16x32_bf16 v[50:53], v[170:173], v[178:181], v[50:53]
	v_mfma_f32_16x16x32_bf16 v[38:41], v[162:165], v[186:189], v[38:41]
	v_mfma_f32_16x16x32_bf16 v[34:37], v[170:173], v[186:189], v[34:37]
	v_mfma_f32_16x16x32_bf16 v[22:25], v[162:165], v[194:197], v[22:25]
	v_mfma_f32_16x16x32_bf16 v[18:21], v[170:173], v[194:197], v[18:21]
	v_mfma_f32_16x16x32_bf16 v[6:9], v[162:165], v[202:205], v[6:9]
	v_mfma_f32_16x16x32_bf16 v[2:5], v[170:173], v[202:205], v[2:5]
	v_mfma_f32_16x16x32_bf16 v[54:57], v[166:169], v[182:185], v[54:57]
	v_mfma_f32_16x16x32_bf16 v[50:53], v[174:177], v[182:185], v[50:53]
	v_mfma_f32_16x16x32_bf16 v[38:41], v[166:169], v[190:193], v[38:41]
	v_mfma_f32_16x16x32_bf16 v[34:37], v[174:177], v[190:193], v[34:37]
	v_mfma_f32_16x16x32_bf16 v[22:25], v[166:169], v[198:201], v[22:25]
	v_mfma_f32_16x16x32_bf16 v[18:21], v[174:177], v[198:201], v[18:21]
	v_mfma_f32_16x16x32_bf16 v[6:9], v[166:169], v[224:227], v[6:9]
	v_mfma_f32_16x16x32_bf16 v[2:5], v[174:177], v[224:227], v[2:5]
	s_barrier
	s_add_u32 s48, s48, 0x100
	s_addc_u32 s49, s49, 0
	s_add_u32 s20, s20, 0x100
	s_addc_u32 s21, s21, 0
	s_cmp_ge_i32 s59, s19
	s_mov_b32 s50, s59
	s_cbranch_scc0 .LBB0_385
	s_setprio 0

; #define PG8_STAGE(bufoff, gbase, voff) do { _Pragma("unroll") for (int _i = 0; _i < 2; ++_i) \
;         __builtin_amdgcn_global_load_lds((const unsigned*)((const char*)(gbase) + (voff)[_i]), (LAS unsigned*)(lds + (bufoff) + ldsw + _i * 8192), 16, 0, 0); } while (0)
; #define PG8_LDA(dst, b, h) do { _Pragma("unroll") for (int m = 0; m < 4; ++m) _Pragma("unroll") for (int k = 0; k < 2; ++k) dst[m][k] = *(const LAS bf16x8*)(lds + PG8_SA(b, h) + aoff + m * 2048 + k * 1024); } while (0)
; #define PG8_LDB(dst, b, h) do { _Pragma("unroll") for (int n = 0; n < 2; ++n) _Pragma("unroll") for (int k = 0; k < 2; ++k) dst[n][k] = *(const LAS bf16x8*)(lds + PG8_SB(b, h) + boff + n * 2048 + k * 1024); } while (0)
; #define PG8_MMA(ai, bj, At, Bt) do { __builtin_amdgcn_s_setprio(1); _Pragma("unroll") for (int m = 0; m < 4; ++m) _Pragma("unroll") for (int n = 0; n < 2; ++n) _Pragma("unroll") for (int k = 0; k < 2; ++k) \
;         acc[ai][bj][m][n] = __builtin_amdgcn_mfma_f32_16x16x32_bf16(Bt[n][k], At[m][k], acc[ai][bj][m][n], 0, 0, 0); __builtin_amdgcn_s_setprio(0); } while (0)
; #define PG8_WAIT_V(n) asm volatile("s_waitcnt vmcnt(" #n ")" ::: "memory")
; #define PG8_WAIT_L(n) asm volatile("s_waitcnt lgkmcnt(" #n ")" ::: "memory")
; #define PG8_BAR __builtin_amdgcn_s_barrier()
; #define PG8_SCHED __builtin_amdgcn_sched_barrier(0)
; template <class Epi>
; __device__ __forceinline__ void gemm_phase(LAS unsigned char* lds, const Gemm g, const Epi& E) {
;     ...
;             const bool last = (t == nt - 2);
;             const char* a1 = cA + (size_t)(t + 1) * kstep;
;             const char* a2 = last ? nA : cA + (size_t)(t + 2) * kstep; const char* b2 = last ? nB : cB + (size_t)(t + 2) * kstep;
;             const char* a3 = a2 + kstep; const char* b3 = b2 + kstep;
;             PG8_LDB(B0, 0, 0); PG8_LDB(B1, 0, 1); PG8_SCHED; PG8_LDA(At, 0, 0); PG8_STAGE(PG8_SA(1, 1), a1 + hstepA, voffA);
;             PG8_WAIT_V(8); PG8_WAIT_L(0); PG8_BAR; PG8_MMA(0, 0, At, B0); PG8_MMA(0, 1, At, B1); PG8_BAR; PG8_SCHED;
;     ...
;         if (!has_next) break;
; #pragma unroll
;         for (int a = 0; a < 2; ++a)
; #pragma unroll
;             for (int b = 0; b < 2; ++b)
; #pragma unroll
;                 for (int m = 0; m < 4; ++m)
; #pragma unroll
;                     for (int n = 0; n < 2; ++n) acc[a][b][m][n] = (f32x4){0.f, 0.f, 0.f, 0.f};
;         cur = nxt; cA = nA; cB = nB; ++ui;
.LBB0_699:
	s_andn2_b64 vcc, exec, s[38:39]
	s_waitcnt lgkmcnt(0)
	s_cbranch_vccnz .LBB0_702
	s_add_u32 s58, s58, 0x80
	s_addc_u32 s59, s59, 0
	s_add_u32 s20, s62, 0x100
	s_addc_u32 s21, s63, 0
	s_mov_b32 s62, 0
	v_mov_b64_e32 v[2:3], 0
	v_mov_b64_e32 v[4:5], 0
	v_mov_b64_e32 v[6:7], 0
	v_mov_b64_e32 v[8:9], 0
	v_mov_b64_e32 v[10:11], 0
	v_mov_b64_e32 v[12:13], 0
	v_mov_b64_e32 v[14:15], 0
	v_mov_b64_e32 v[16:17], 0
	v_mov_b64_e32 v[18:19], 0
	v_mov_b64_e32 v[20:21], 0
	v_mov_b64_e32 v[22:23], 0
	v_mov_b64_e32 v[24:25], 0
	v_mov_b64_e32 v[26:27], 0
	v_mov_b64_e32 v[28:29], 0
	v_mov_b64_e32 v[30:31], 0
	v_mov_b64_e32 v[32:33], 0
	v_mov_b64_e32 v[34:35], 0
	v_mov_b64_e32 v[36:37], 0
	v_mov_b64_e32 v[38:39], 0
	v_mov_b64_e32 v[40:41], 0
	v_mov_b64_e32 v[42:43], 0
	v_mov_b64_e32 v[44:45], 0
	v_mov_b64_e32 v[46:47], 0
	v_mov_b64_e32 v[48:49], 0
	v_mov_b64_e32 v[50:51], 0
	v_mov_b64_e32 v[52:53], 0
	v_mov_b64_e32 v[54:55], 0
	v_mov_b64_e32 v[56:57], 0
	v_mov_b64_e32 v[58:59], 0
	v_mov_b64_e32 v[60:61], 0
	v_mov_b64_e32 v[62:63], 0
	v_mov_b64_e32 v[64:65], 0
	v_mov_b64_e32 v[66:67], 0
	v_mov_b64_e32 v[68:69], 0
	v_mov_b64_e32 v[70:71], 0
	v_mov_b64_e32 v[72:73], 0
	v_mov_b64_e32 v[74:75], 0
	v_mov_b64_e32 v[76:77], 0
	v_mov_b64_e32 v[78:79], 0
	v_mov_b64_e32 v[80:81], 0
	v_mov_b64_e32 v[82:83], 0
	v_mov_b64_e32 v[84:85], 0
	v_mov_b64_e32 v[86:87], 0
	v_mov_b64_e32 v[88:89], 0
	v_mov_b64_e32 v[90:91], 0
	v_mov_b64_e32 v[92:93], 0
	v_mov_b64_e32 v[94:95], 0
	v_mov_b64_e32 v[96:97], 0
	v_mov_b64_e32 v[98:99], 0
	v_mov_b64_e32 v[100:101], 0
	v_mov_b64_e32 v[102:103], 0
	v_mov_b64_e32 v[104:105], 0
	v_mov_b64_e32 v[106:107], 0
	v_mov_b64_e32 v[108:109], 0
	v_mov_b64_e32 v[110:111], 0
	v_mov_b64_e32 v[112:113], 0
	v_mov_b64_e32 v[114:115], 0
	v_mov_b64_e32 v[116:117], 0
	v_mov_b64_e32 v[118:119], 0
	v_mov_b64_e32 v[120:121], 0
	v_mov_b64_e32 v[122:123], 0
	v_mov_b64_e32 v[124:125], 0
	v_mov_b64_e32 v[126:127], 0
	v_mov_b64_e32 v[128:129], 0
	s_and_b64 vcc, exec, s[48:49]
	s_cbranch_vccnz .Lg701_prio_skip
	s_setprio 1
.Lg701_prio_skip:
.LBB0_701:
	s_add_i32 s70, s62, 2
	s_add_u32 s71, s58, 0x80
	s_addc_u32 s63, s59, 0
	s_add_i32 s72, 0, 0x10000
	s_cmp_eq_u32 s35, s62
	s_cselect_b32 s63, s47, s63
	s_cselect_b32 s62, s46, s71
	v_add_u32_e32 v144, s72, v147
	s_cselect_b32 s75, s53, s21
	s_cselect_b32 s74, s52, s20
	s_add_i32 s71, 0, 0x14000
	ds_read_b128 v[140:143], v144
	ds_read_b128 v[154:157], v144 offset:1024
	ds_read_b128 v[158:161], v144 offset:2048
	ds_read_b128 v[162:165], v144 offset:3072
	v_add_u32_e32 v144, s71, v147
	ds_read_b128 v[166:169], v144
	ds_read_b128 v[170:173], v144 offset:1024
	ds_read_b128 v[174:177], v144 offset:2048
	ds_read_b128 v[178:181], v144 offset:3072
	v_lshl_add_u64 v[144:145], s[58:59], 0, v[136:137]
	s_add_i32 m0, s7, 0xc000
	ds_read_b128 v[182:185], v151
	ds_read_b128 v[186:189], v151 offset:1024
	ds_read_b128 v[190:193], v151 offset:2048
	ds_read_b128 v[194:197], v151 offset:3072
	ds_read_b128 v[198:201], v151 offset:4096
	ds_read_b128 v[202:205], v151 offset:5120
	ds_read_b128 v[224:227], v151 offset:6144
	ds_read_b128 v[228:231], v151 offset:7168
	global_load_lds_dwordx4 v[144:145], off
	v_lshl_add_u64 v[144:145], s[58:59], 0, v[138:139]
	s_add_i32 m0, s7, 0xe000
	s_nop 0
	global_load_lds_dwordx4 v[144:145], off
	s_waitcnt vmcnt(8)
	s_waitcnt lgkmcnt(0)
	s_barrier
	s_waitcnt lgkmcnt(0)
	v_mfma_f32_16x16x32_bf16 v[126:129], v[140:143], v[182:185], v[126:129]
	v_mfma_f32_16x16x32_bf16 v[122:125], v[158:161], v[182:185], v[122:125]
	v_mfma_f32_16x16x32_bf16 v[110:113], v[140:143], v[190:193], v[110:113]
	v_mfma_f32_16x16x32_bf16 v[106:109], v[158:161], v[190:193], v[106:109]
	v_mfma_f32_16x16x32_bf16 v[94:97], v[140:143], v[198:201], v[94:97]
	v_mfma_f32_16x16x32_bf16 v[90:93], v[158:161], v[198:201], v[90:93]
	v_mfma_f32_16x16x32_bf16 v[78:81], v[140:143], v[224:227], v[78:81]
	v_mfma_f32_16x16x32_bf16 v[74:77], v[158:161], v[224:227], v[74:77]
	v_mfma_f32_16x16x32_bf16 v[126:129], v[154:157], v[186:189], v[126:129]
	v_mfma_f32_16x16x32_bf16 v[122:125], v[162:165], v[186:189], v[122:125]
	v_mfma_f32_16x16x32_bf16 v[110:113], v[154:157], v[194:197], v[110:113]
	v_mfma_f32_16x16x32_bf16 v[106:109], v[162:165], v[194:197], v[106:109]
	v_mfma_f32_16x16x32_bf16 v[94:97], v[154:157], v[202:205], v[94:97]
	v_mfma_f32_16x16x32_bf16 v[90:93], v[162:165], v[202:205], v[90:93]
	v_mfma_f32_16x16x32_bf16 v[78:81], v[154:157], v[228:231], v[78:81]
	v_mfma_f32_16x16x32_bf16 v[74:77], v[162:165], v[228:231], v[74:77]
	v_mfma_f32_16x16x32_bf16 v[118:121], v[166:169], v[182:185], v[118:121]
	v_mfma_f32_16x16x32_bf16 v[114:117], v[174:177], v[182:185], v[114:117]
	v_mfma_f32_16x16x32_bf16 v[102:105], v[166:169], v[190:193], v[102:105]
	v_mfma_f32_16x16x32_bf16 v[98:101], v[174:177], v[190:193], v[98:101]
	v_mfma_f32_16x16x32_bf16 v[86:89], v[166:169], v[198:201], v[86:89]
	v_mfma_f32_16x16x32_bf16 v[82:85], v[174:177], v[198:201], v[82:85]
	v_mfma_f32_16x16x32_bf16 v[70:73], v[166:169], v[224:227], v[70:73]
	v_mfma_f32_16x16x32_bf16 v[66:69], v[174:177], v[224:227], v[66:69]
	v_mfma_f32_16x16x32_bf16 v[118:121], v[170:173], v[186:189], v[118:121]
	v_mfma_f32_16x16x32_bf16 v[114:117], v[178:181], v[186:189], v[114:117]
	v_mfma_f32_16x16x32_bf16 v[102:105], v[170:173], v[194:197], v[102:105]
	v_mfma_f32_16x16x32_bf16 v[98:101], v[178:181], v[194:197], v[98:101]
	v_mfma_f32_16x16x32_bf16 v[86:89], v[170:173], v[202:205], v[86:89]
	v_mfma_f32_16x16x32_bf16 v[82:85], v[178:181], v[202:205], v[82:85]
	v_mfma_f32_16x16x32_bf16 v[70:73], v[170:173], v[228:231], v[70:73]
	v_mfma_f32_16x16x32_bf16 v[66:69], v[178:181], v[228:231], v[66:69]
	s_barrier
; #define PG8_STAGE(bufoff, gbase, voff) do { _Pragma("unroll") for (int _i = 0; _i < 2; ++_i) \
;         __builtin_amdgcn_global_load_lds((const unsigned*)((const char*)(gbase) + (voff)[_i]), (LAS unsigned*)(lds + (bufoff) + ldsw + _i * 8192), 16, 0, 0); } while (0)
; #define PG8_LDA(dst, b, h) do { _Pragma("unroll") for (int m = 0; m < 4; ++m) _Pragma("unroll") for (int k = 0; k < 2; ++k) dst[m][k] = *(const LAS bf16x8*)(lds + PG8_SA(b, h) + aoff + m * 2048 + k * 1024); } while (0)
; #define PG8_LDB(dst, b, h) do { _Pragma("unroll") for (int n = 0; n < 2; ++n) _Pragma("unroll") for (int k = 0; k < 2; ++k) dst[n][k] = *(const LAS bf16x8*)(lds + PG8_SB(b, h) + boff + n * 2048 + k * 1024); } while (0)
; #define PG8_MMA(ai, bj, At, Bt) do { __builtin_amdgcn_s_setprio(1); _Pragma("unroll") for (int m = 0; m < 4; ++m) _Pragma("unroll") for (int n = 0; n < 2; ++n) _Pragma("unroll") for (int k = 0; k < 2; ++k) \
;         acc[ai][bj][m][n] = __builtin_amdgcn_mfma_f32_16x16x32_bf16(Bt[n][k], At[m][k], acc[ai][bj][m][n], 0, 0, 0); __builtin_amdgcn_s_setprio(0); } while (0)
; #define PG8_WAIT_V(n) asm volatile("s_waitcnt vmcnt(" #n ")" ::: "memory")
; #define PG8_WAIT_L(n) asm volatile("s_waitcnt lgkmcnt(" #n ")" ::: "memory")
; #define PG8_BAR __builtin_amdgcn_s_barrier()
; #define PG8_SCHED __builtin_amdgcn_sched_barrier(0)
; template <class Epi>
; __device__ __forceinline__ void gemm_phase(LAS unsigned char* lds, const Gemm g, const Epi& E) {
;     ...
;             PG8_LDA(At, 0, 1); PG8_STAGE(PG8_SB(0, 0), b2, voffB); PG8_STAGE(PG8_SB(0, 1), b2 + hstepB, voffB); PG8_STAGE(PG8_SA(0, 0), a2, voffA);
;             PG8_WAIT_V(8); PG8_WAIT_L(0); PG8_BAR; PG8_MMA(1, 0, At, B0); PG8_MMA(1, 1, At, B1); PG8_BAR; PG8_SCHED;
;             PG8_LDB(B0, 1, 0); PG8_LDB(B1, 1, 1); PG8_SCHED; PG8_LDA(At, 1, 0); PG8_STAGE(PG8_SA(0, 1), a2 + hstepA, voffA);
	s_add_i32 s72, s72, s6
	v_lshl_add_u64 v[144:145], s[74:75], 0, v[0:1]
	s_mov_b32 m0, s72
	ds_read_b128 v[182:185], v151 offset:16384
	ds_read_b128 v[186:189], v151 offset:17408
	ds_read_b128 v[190:193], v151 offset:18432
	ds_read_b128 v[194:197], v151 offset:19456
	ds_read_b128 v[198:201], v151 offset:20480
	ds_read_b128 v[202:205], v151 offset:21504
	ds_read_b128 v[224:227], v151 offset:22528
	ds_read_b128 v[228:231], v151 offset:23552
	global_load_lds_dwordx4 v[144:145], off
	s_add_i32 m0, s72, 0x2000
	v_lshl_add_u64 v[206:207], s[74:75], 0, v[130:131]
	s_add_u32 s74, s74, s10
	s_addc_u32 s75, s75, s11
	s_add_i32 s71, s71, s6
	global_load_lds_dwordx4 v[206:207], off
	v_lshl_add_u64 v[220:221], s[74:75], 0, v[0:1]
	s_mov_b32 m0, s71
	v_lshl_add_u64 v[222:223], s[74:75], 0, v[130:131]
	global_load_lds_dwordx4 v[220:221], off
	s_add_i32 m0, s71, 0x2000
	v_lshl_add_u64 v[232:233], s[62:63], 0, v[134:135]
	global_load_lds_dwordx4 v[222:223], off
	s_mov_b32 m0, s7
	v_lshl_add_u64 v[242:243], s[62:63], 0, v[132:133]
	global_load_lds_dwordx4 v[232:233], off
	s_mov_b32 m0, s8
	s_nop 0
	global_load_lds_dwordx4 v[242:243], off
	s_waitcnt vmcnt(8)
	s_waitcnt lgkmcnt(0)
	s_barrier
	s_waitcnt lgkmcnt(0)
	v_mfma_f32_16x16x32_bf16 v[62:65], v[140:143], v[182:185], v[62:65]
	v_mfma_f32_16x16x32_bf16 v[58:61], v[158:161], v[182:185], v[58:61]
	v_mfma_f32_16x16x32_bf16 v[46:49], v[140:143], v[190:193], v[46:49]
	v_mfma_f32_16x16x32_bf16 v[42:45], v[158:161], v[190:193], v[42:45]
	v_mfma_f32_16x16x32_bf16 v[30:33], v[140:143], v[198:201], v[30:33]
	v_mfma_f32_16x16x32_bf16 v[26:29], v[158:161], v[198:201], v[26:29]
	v_mfma_f32_16x16x32_bf16 v[14:17], v[140:143], v[224:227], v[14:17]
	v_mfma_f32_16x16x32_bf16 v[10:13], v[158:161], v[224:227], v[10:13]
	v_mfma_f32_16x16x32_bf16 v[62:65], v[154:157], v[186:189], v[62:65]
	v_mfma_f32_16x16x32_bf16 v[58:61], v[162:165], v[186:189], v[58:61]
	v_mfma_f32_16x16x32_bf16 v[46:49], v[154:157], v[194:197], v[46:49]
	v_mfma_f32_16x16x32_bf16 v[42:45], v[162:165], v[194:197], v[42:45]
	v_mfma_f32_16x16x32_bf16 v[30:33], v[154:157], v[202:205], v[30:33]
	v_mfma_f32_16x16x32_bf16 v[26:29], v[162:165], v[202:205], v[26:29]
	v_mfma_f32_16x16x32_bf16 v[14:17], v[154:157], v[228:231], v[14:17]
	v_mfma_f32_16x16x32_bf16 v[10:13], v[162:165], v[228:231], v[10:13]
	v_mfma_f32_16x16x32_bf16 v[54:57], v[166:169], v[182:185], v[54:57]
	v_mfma_f32_16x16x32_bf16 v[50:53], v[174:177], v[182:185], v[50:53]
	v_mfma_f32_16x16x32_bf16 v[38:41], v[166:169], v[190:193], v[38:41]
	v_mfma_f32_16x16x32_bf16 v[34:37], v[174:177], v[190:193], v[34:37]
	v_mfma_f32_16x16x32_bf16 v[22:25], v[166:169], v[198:201], v[22:25]
	v_mfma_f32_16x16x32_bf16 v[18:21], v[174:177], v[198:201], v[18:21]
	v_mfma_f32_16x16x32_bf16 v[6:9], v[166:169], v[224:227], v[6:9]
	v_mfma_f32_16x16x32_bf16 v[2:5], v[174:177], v[224:227], v[2:5]
	v_mfma_f32_16x16x32_bf16 v[54:57], v[170:173], v[186:189], v[54:57]
	v_mfma_f32_16x16x32_bf16 v[50:53], v[178:181], v[186:189], v[50:53]
	v_mfma_f32_16x16x32_bf16 v[38:41], v[170:173], v[194:197], v[38:41]
	v_mfma_f32_16x16x32_bf16 v[34:37], v[178:181], v[194:197], v[34:37]
	v_mfma_f32_16x16x32_bf16 v[22:25], v[170:173], v[202:205], v[22:25]
	v_mfma_f32_16x16x32_bf16 v[18:21], v[178:181], v[202:205], v[18:21]
	v_mfma_f32_16x16x32_bf16 v[6:9], v[170:173], v[228:231], v[6:9]
	v_mfma_f32_16x16x32_bf16 v[2:5], v[178:181], v[228:231], v[2:5]
	s_barrier
	s_add_i32 s71, 0, 0x18000
	v_add_u32_e32 v153, s71, v147
	s_add_i32 s72, 0, 0x1c000
	ds_read_b128 v[140:143], v153
	ds_read_b128 v[154:157], v153 offset:1024
	ds_read_b128 v[158:161], v153 offset:2048
	ds_read_b128 v[162:165], v153 offset:3072
	v_add_u32_e32 v153, s72, v147
	ds_read_b128 v[166:169], v153
	ds_read_b128 v[170:173], v153 offset:1024
	ds_read_b128 v[174:177], v153 offset:2048
	ds_read_b128 v[178:181], v153 offset:3072
	s_add_u32 s62, s62, s0
	s_addc_u32 s63, s63, s1
	s_mov_b32 m0, s9
	v_lshl_add_u64 v[244:245], s[62:63], 0, v[134:135]
	ds_read_b128 v[182:185], v151 offset:32768
	ds_read_b128 v[186:189], v151 offset:33792
	ds_read_b128 v[190:193], v151 offset:34816
	ds_read_b128 v[194:197], v151 offset:35840
	ds_read_b128 v[198:201], v151 offset:36864
	ds_read_b128 v[202:205], v151 offset:37888
	ds_read_b128 v[224:227], v151 offset:38912
	ds_read_b128 v[228:231], v151 offset:39936
	global_load_lds_dwordx4 v[244:245], off
	v_lshl_add_u64 v[244:245], s[62:63], 0, v[132:133]
	s_mov_b32 m0, s18
	s_nop 0
	global_load_lds_dwordx4 v[244:245], off
	s_waitcnt vmcnt(8)
	s_waitcnt lgkmcnt(0)
	s_barrier
; #define PG8_STAGE(bufoff, gbase, voff) do { _Pragma("unroll") for (int _i = 0; _i < 2; ++_i) \
;         __builtin_amdgcn_global_load_lds((const unsigned*)((const char*)(gbase) + (voff)[_i]), (LAS unsigned*)(lds + (bufoff) + ldsw + _i * 8192), 16, 0, 0); } while (0)
; #define PG8_LDA(dst, b, h) do { _Pragma("unroll") for (int m = 0; m < 4; ++m) _Pragma("unroll") for (int k = 0; k < 2; ++k) dst[m][k] = *(const LAS bf16x8*)(lds + PG8_SA(b, h) + aoff + m * 2048 + k * 1024); } while (0)
; #define PG8_MMA(ai, bj, At, Bt) do { __builtin_amdgcn_s_setprio(1); _Pragma("unroll") for (int m = 0; m < 4; ++m) _Pragma("unroll") for (int n = 0; n < 2; ++n) _Pragma("unroll") for (int k = 0; k < 2; ++k) \
;         acc[ai][bj][m][n] = __builtin_amdgcn_mfma_f32_16x16x32_bf16(Bt[n][k], At[m][k], acc[ai][bj][m][n], 0, 0, 0); __builtin_amdgcn_s_setprio(0); } while (0)
; #define PG8_WAIT_V(n) asm volatile("s_waitcnt vmcnt(" #n ")" ::: "memory")
; #define PG8_WAIT_L(n) asm volatile("s_waitcnt lgkmcnt(" #n ")" ::: "memory")
; #define PG8_BAR __builtin_amdgcn_s_barrier()
; #define PG8_SCHED __builtin_amdgcn_sched_barrier(0)
; template <class Epi>
; __device__ __forceinline__ void gemm_phase(LAS unsigned char* lds, const Gemm g, const Epi& E) {
;     ...
;             PG8_WAIT_V(8); PG8_WAIT_L(0); PG8_BAR; PG8_MMA(0, 0, At, B0); PG8_MMA(0, 1, At, B1); PG8_BAR; PG8_SCHED;
;             PG8_LDA(At, 1, 1); PG8_STAGE(PG8_SB(1, 0), b3, voffB); PG8_STAGE(PG8_SB(1, 1), b3 + hstepB, voffB); PG8_STAGE(PG8_SA(1, 0), a3, voffA);
;             PG8_WAIT_V(8); PG8_WAIT_L(0); PG8_BAR; PG8_MMA(1, 0, At, B0); PG8_MMA(1, 1, At, B1); PG8_BAR; PG8_SCHED;
;         }
	s_waitcnt lgkmcnt(0)
	v_mfma_f32_16x16x32_bf16 v[126:129], v[140:143], v[182:185], v[126:129]
	v_mfma_f32_16x16x32_bf16 v[122:125], v[158:161], v[182:185], v[122:125]
	v_mfma_f32_16x16x32_bf16 v[110:113], v[140:143], v[190:193], v[110:113]
	v_mfma_f32_16x16x32_bf16 v[106:109], v[158:161], v[190:193], v[106:109]
	v_mfma_f32_16x16x32_bf16 v[94:97], v[140:143], v[198:201], v[94:97]
	v_mfma_f32_16x16x32_bf16 v[90:93], v[158:161], v[198:201], v[90:93]
	v_mfma_f32_16x16x32_bf16 v[78:81], v[140:143], v[224:227], v[78:81]
	v_mfma_f32_16x16x32_bf16 v[74:77], v[158:161], v[224:227], v[74:77]
	v_mfma_f32_16x16x32_bf16 v[126:129], v[154:157], v[186:189], v[126:129]
	v_mfma_f32_16x16x32_bf16 v[122:125], v[162:165], v[186:189], v[122:125]
	v_mfma_f32_16x16x32_bf16 v[110:113], v[154:157], v[194:197], v[110:113]
	v_mfma_f32_16x16x32_bf16 v[106:109], v[162:165], v[194:197], v[106:109]
	v_mfma_f32_16x16x32_bf16 v[94:97], v[154:157], v[202:205], v[94:97]
	v_mfma_f32_16x16x32_bf16 v[90:93], v[162:165], v[202:205], v[90:93]
	v_mfma_f32_16x16x32_bf16 v[78:81], v[154:157], v[228:231], v[78:81]
	v_mfma_f32_16x16x32_bf16 v[74:77], v[162:165], v[228:231], v[74:77]
	v_mfma_f32_16x16x32_bf16 v[118:121], v[166:169], v[182:185], v[118:121]
	v_mfma_f32_16x16x32_bf16 v[114:117], v[174:177], v[182:185], v[114:117]
	v_mfma_f32_16x16x32_bf16 v[102:105], v[166:169], v[190:193], v[102:105]
	v_mfma_f32_16x16x32_bf16 v[98:101], v[174:177], v[190:193], v[98:101]
	v_mfma_f32_16x16x32_bf16 v[86:89], v[166:169], v[198:201], v[86:89]
	v_mfma_f32_16x16x32_bf16 v[82:85], v[174:177], v[198:201], v[82:85]
	v_mfma_f32_16x16x32_bf16 v[70:73], v[166:169], v[224:227], v[70:73]
	v_mfma_f32_16x16x32_bf16 v[66:69], v[174:177], v[224:227], v[66:69]
	v_mfma_f32_16x16x32_bf16 v[118:121], v[170:173], v[186:189], v[118:121]
	v_mfma_f32_16x16x32_bf16 v[114:117], v[178:181], v[186:189], v[114:117]
	v_mfma_f32_16x16x32_bf16 v[102:105], v[170:173], v[194:197], v[102:105]
	v_mfma_f32_16x16x32_bf16 v[98:101], v[178:181], v[194:197], v[98:101]
	v_mfma_f32_16x16x32_bf16 v[86:89], v[170:173], v[202:205], v[86:89]
	v_mfma_f32_16x16x32_bf16 v[82:85], v[178:181], v[202:205], v[82:85]
	v_mfma_f32_16x16x32_bf16 v[70:73], v[170:173], v[228:231], v[70:73]
	v_mfma_f32_16x16x32_bf16 v[66:69], v[178:181], v[228:231], v[66:69]
	s_barrier
	s_add_i32 s62, s71, s6
	v_lshl_add_u64 v[144:145], v[144:145], 0, s[28:29]
	s_mov_b32 m0, s62
	ds_read_b128 v[182:185], v151 offset:49152
	ds_read_b128 v[186:189], v151 offset:50176
	ds_read_b128 v[190:193], v151 offset:51200
	ds_read_b128 v[194:197], v151 offset:52224
	ds_read_b128 v[198:201], v151 offset:53248
	ds_read_b128 v[202:205], v151 offset:54272
	ds_read_b128 v[224:227], v151 offset:55296
	ds_read_b128 v[228:231], v151 offset:56320
	global_load_lds_dwordx4 v[144:145], off
	v_lshl_add_u64 v[144:145], v[206:207], 0, s[28:29]
	s_add_i32 m0, s62, 0x2000
	s_add_i32 s62, s72, s6
	global_load_lds_dwordx4 v[144:145], off
	v_lshl_add_u64 v[144:145], v[220:221], 0, s[28:29]
	s_mov_b32 m0, s62
	s_nop 0
	global_load_lds_dwordx4 v[144:145], off
	v_lshl_add_u64 v[144:145], v[222:223], 0, s[28:29]
	s_add_i32 m0, s62, 0x2000
	s_nop 0
	global_load_lds_dwordx4 v[144:145], off
	v_lshl_add_u64 v[144:145], v[232:233], 0, s[28:29]
	s_mov_b32 m0, s19
	s_nop 0
	global_load_lds_dwordx4 v[144:145], off
	v_lshl_add_u64 v[144:145], v[242:243], 0, s[28:29]
	s_mov_b32 m0, s24
	s_nop 0
	global_load_lds_dwordx4 v[144:145], off
	s_waitcnt vmcnt(8)
	s_waitcnt lgkmcnt(0)
	s_barrier
	s_waitcnt lgkmcnt(0)
	v_mfma_f32_16x16x32_bf16 v[62:65], v[140:143], v[182:185], v[62:65]
	v_mfma_f32_16x16x32_bf16 v[58:61], v[158:161], v[182:185], v[58:61]
	v_mfma_f32_16x16x32_bf16 v[46:49], v[140:143], v[190:193], v[46:49]
	v_mfma_f32_16x16x32_bf16 v[42:45], v[158:161], v[190:193], v[42:45]
	v_mfma_f32_16x16x32_bf16 v[30:33], v[140:143], v[198:201], v[30:33]
	v_mfma_f32_16x16x32_bf16 v[26:29], v[158:161], v[198:201], v[26:29]
	v_mfma_f32_16x16x32_bf16 v[14:17], v[140:143], v[224:227], v[14:17]
	v_mfma_f32_16x16x32_bf16 v[10:13], v[158:161], v[224:227], v[10:13]
	v_mfma_f32_16x16x32_bf16 v[62:65], v[154:157], v[186:189], v[62:65]
	v_mfma_f32_16x16x32_bf16 v[58:61], v[162:165], v[186:189], v[58:61]
	v_mfma_f32_16x16x32_bf16 v[46:49], v[154:157], v[194:197], v[46:49]
	v_mfma_f32_16x16x32_bf16 v[42:45], v[162:165], v[194:197], v[42:45]
	v_mfma_f32_16x16x32_bf16 v[30:33], v[154:157], v[202:205], v[30:33]
	v_mfma_f32_16x16x32_bf16 v[26:29], v[162:165], v[202:205], v[26:29]
	v_mfma_f32_16x16x32_bf16 v[14:17], v[154:157], v[228:231], v[14:17]
	v_mfma_f32_16x16x32_bf16 v[10:13], v[162:165], v[228:231], v[10:13]
	v_mfma_f32_16x16x32_bf16 v[54:57], v[166:169], v[182:185], v[54:57]
	v_mfma_f32_16x16x32_bf16 v[50:53], v[174:177], v[182:185], v[50:53]
	v_mfma_f32_16x16x32_bf16 v[38:41], v[166:169], v[190:193], v[38:41]
	v_mfma_f32_16x16x32_bf16 v[34:37], v[174:177], v[190:193], v[34:37]
	v_mfma_f32_16x16x32_bf16 v[22:25], v[166:169], v[198:201], v[22:25]
	v_mfma_f32_16x16x32_bf16 v[18:21], v[174:177], v[198:201], v[18:21]
	v_mfma_f32_16x16x32_bf16 v[6:9], v[166:169], v[224:227], v[6:9]
	v_mfma_f32_16x16x32_bf16 v[2:5], v[174:177], v[224:227], v[2:5]
	v_mfma_f32_16x16x32_bf16 v[54:57], v[170:173], v[186:189], v[54:57]
	v_mfma_f32_16x16x32_bf16 v[50:53], v[178:181], v[186:189], v[50:53]
	v_mfma_f32_16x16x32_bf16 v[38:41], v[170:173], v[194:197], v[38:41]
	v_mfma_f32_16x16x32_bf16 v[34:37], v[178:181], v[194:197], v[34:37]
	v_mfma_f32_16x16x32_bf16 v[22:25], v[170:173], v[202:205], v[22:25]
	v_mfma_f32_16x16x32_bf16 v[18:21], v[178:181], v[202:205], v[18:21]
	v_mfma_f32_16x16x32_bf16 v[6:9], v[170:173], v[228:231], v[6:9]
	v_mfma_f32_16x16x32_bf16 v[2:5], v[178:181], v[228:231], v[2:5]
	s_barrier
	s_add_u32 s58, s58, 0x100
	s_addc_u32 s59, s59, 0
	s_add_u32 s20, s20, 0x100
	s_addc_u32 s21, s21, 0
	s_cmp_ge_i32 s70, s25
	s_mov_b32 s62, s70
	s_cbranch_scc0 .LBB0_701
	s_setprio 0

; #define PG8_STAGE(bufoff, gbase, voff) do { _Pragma("unroll") for (int _i = 0; _i < 2; ++_i) \
;         __builtin_amdgcn_global_load_lds((const unsigned*)((const char*)(gbase) + (voff)[_i]), (LAS unsigned*)(lds + (bufoff) + ldsw + _i * 8192), 16, 0, 0); } while (0)
; #define PG8_LDA(dst, b, h) do { _Pragma("unroll") for (int m = 0; m < 4; ++m) _Pragma("unroll") for (int k = 0; k < 2; ++k) dst[m][k] = *(const LAS bf16x8*)(lds + PG8_SA(b, h) + aoff + m * 2048 + k * 1024); } while (0)
; #define PG8_LDB(dst, b, h) do { _Pragma("unroll") for (int n = 0; n < 2; ++n) _Pragma("unroll") for (int k = 0; k < 2; ++k) dst[n][k] = *(const LAS bf16x8*)(lds + PG8_SB(b, h) + boff + n * 2048 + k * 1024); } while (0)
; #define PG8_MMA(ai, bj, At, Bt) do { __builtin_amdgcn_s_setprio(1); _Pragma("unroll") for (int m = 0; m < 4; ++m) _Pragma("unroll") for (int n = 0; n < 2; ++n) _Pragma("unroll") for (int k = 0; k < 2; ++k) \
;         acc[ai][bj][m][n] = __builtin_amdgcn_mfma_f32_16x16x32_bf16(Bt[n][k], At[m][k], acc[ai][bj][m][n], 0, 0, 0); __builtin_amdgcn_s_setprio(0); } while (0)
; #define PG8_WAIT_V(n) asm volatile("s_waitcnt vmcnt(" #n ")" ::: "memory")
; #define PG8_WAIT_L(n) asm volatile("s_waitcnt lgkmcnt(" #n ")" ::: "memory")
; #define PG8_BAR __builtin_amdgcn_s_barrier()
; #define PG8_SCHED __builtin_amdgcn_sched_barrier(0)
; template <class Epi>
; __device__ __forceinline__ void gemm_phase(LAS unsigned char* lds, const Gemm g, const Epi& E) {
;     ...
;             const bool last = (t == nt - 2);
;             const char* a1 = cA + (size_t)(t + 1) * kstep;
;             const char* a2 = last ? nA : cA + (size_t)(t + 2) * kstep; const char* b2 = last ? nB : cB + (size_t)(t + 2) * kstep;
;             const char* a3 = a2 + kstep; const char* b3 = b2 + kstep;
;             PG8_LDB(B0, 0, 0); PG8_LDB(B1, 0, 1); PG8_SCHED; PG8_LDA(At, 0, 0); PG8_STAGE(PG8_SA(1, 1), a1 + hstepA, voffA);
;             PG8_WAIT_V(8); PG8_WAIT_L(0); PG8_BAR; PG8_MMA(0, 0, At, B0); PG8_MMA(0, 1, At, B1); PG8_BAR; PG8_SCHED;
;     ...
; #pragma unroll
;         for (int a = 0; a < 2; ++a)
; #pragma unroll
;             for (int b = 0; b < 2; ++b)
; #pragma unroll
;                 for (int m = 0; m < 4; ++m)
; #pragma unroll
;                     for (int n = 0; n < 2; ++n) acc[a][b][m][n] = (f32x4){0.f, 0.f, 0.f, 0.f};
;         cur = nxt; cA = nA; cB = nB; ++ui;
.Lup_ssq_skip:
	s_add_u32 s46, s50, 0x80
	s_addc_u32 s47, s51, 0
	s_add_u32 s24, s48, 0x100
	s_addc_u32 s25, s49, 0
	s_mov_b32 s48, 0
	v_mov_b64_e32 v[2:3], 0
	v_mov_b64_e32 v[4:5], 0
	v_mov_b64_e32 v[6:7], 0
	v_mov_b64_e32 v[8:9], 0
	v_mov_b64_e32 v[10:11], 0
	v_mov_b64_e32 v[12:13], 0
	v_mov_b64_e32 v[14:15], 0
	v_mov_b64_e32 v[16:17], 0
	v_mov_b64_e32 v[18:19], 0
	v_mov_b64_e32 v[20:21], 0
	v_mov_b64_e32 v[22:23], 0
	v_mov_b64_e32 v[24:25], 0
	v_mov_b64_e32 v[26:27], 0
	v_mov_b64_e32 v[28:29], 0
	v_mov_b64_e32 v[30:31], 0
	v_mov_b64_e32 v[32:33], 0
	v_mov_b64_e32 v[34:35], 0
	v_mov_b64_e32 v[36:37], 0
	v_mov_b64_e32 v[38:39], 0
	v_mov_b64_e32 v[40:41], 0
	v_mov_b64_e32 v[42:43], 0
	v_mov_b64_e32 v[44:45], 0
	v_mov_b64_e32 v[46:47], 0
	v_mov_b64_e32 v[48:49], 0
	v_mov_b64_e32 v[50:51], 0
	v_mov_b64_e32 v[52:53], 0
	v_mov_b64_e32 v[54:55], 0
	v_mov_b64_e32 v[56:57], 0
	v_mov_b64_e32 v[58:59], 0
	v_mov_b64_e32 v[60:61], 0
	v_mov_b64_e32 v[62:63], 0
	v_mov_b64_e32 v[64:65], 0
	v_mov_b64_e32 v[66:67], 0
	v_mov_b64_e32 v[68:69], 0
	v_mov_b64_e32 v[70:71], 0
	v_mov_b64_e32 v[72:73], 0
	v_mov_b64_e32 v[74:75], 0
	v_mov_b64_e32 v[76:77], 0
	v_mov_b64_e32 v[78:79], 0
	v_mov_b64_e32 v[80:81], 0
	v_mov_b64_e32 v[82:83], 0
	v_mov_b64_e32 v[84:85], 0
	v_mov_b64_e32 v[86:87], 0
	v_mov_b64_e32 v[88:89], 0
	v_mov_b64_e32 v[90:91], 0
	v_mov_b64_e32 v[92:93], 0
	v_mov_b64_e32 v[94:95], 0
	v_mov_b64_e32 v[96:97], 0
	v_mov_b64_e32 v[98:99], 0
	v_mov_b64_e32 v[100:101], 0
	v_mov_b64_e32 v[102:103], 0
	v_mov_b64_e32 v[104:105], 0
	v_mov_b64_e32 v[106:107], 0
	v_mov_b64_e32 v[108:109], 0
	v_mov_b64_e32 v[110:111], 0
	v_mov_b64_e32 v[112:113], 0
	v_mov_b64_e32 v[114:115], 0
	v_mov_b64_e32 v[116:117], 0
	v_mov_b64_e32 v[118:119], 0
	v_mov_b64_e32 v[120:121], 0
	v_mov_b64_e32 v[122:123], 0
	v_mov_b64_e32 v[124:125], 0
	v_mov_b64_e32 v[126:127], 0
	v_mov_b64_e32 v[128:129], 0
	s_cmp_lg_u32 s54, 1
	s_cbranch_scc1 .Lg792_prio_skip
	s_setprio 1
.Lg792_prio_skip:
.LBB0_792:
	s_add_i32 s50, s48, 2
	s_add_u32 s51, s46, 0x80
	s_addc_u32 s49, s47, 0
	s_add_i32 vcc_lo, 0, 0x10000
	s_cmp_eq_u32 s35, s48
	s_cselect_b32 s49, s59, s49
	s_cselect_b32 s48, s58, s51
	s_cselect_b32 s53, s17, s25
	s_cselect_b32 s52, s16, s24
	s_add_i32 s51, 0, 0x14000
	v_add_u32_e32 v156, vcc_lo, v241
	v_add_u32_e32 v172, s51, v241
	ds_read_b128 v[144:147], v156
	ds_read_b128 v[148:151], v156 offset:1024
	ds_read_b128 v[152:155], v156 offset:2048
	ds_read_b128 v[156:159], v156 offset:3072
	ds_read_b128 v[160:163], v172
	ds_read_b128 v[164:167], v172 offset:1024
	ds_read_b128 v[168:171], v172 offset:2048
	ds_read_b128 v[172:175], v172 offset:3072
	v_lshl_add_u64 v[220:221], s[46:47], 0, v[140:141]
	s_add_i32 m0, s6, 0xc000
	ds_read_b128 v[176:179], v243
	ds_read_b128 v[180:183], v243 offset:1024
	ds_read_b128 v[184:187], v243 offset:2048
	ds_read_b128 v[188:191], v243 offset:3072
	ds_read_b128 v[192:195], v243 offset:4096
	ds_read_b128 v[196:199], v243 offset:5120
	ds_read_b128 v[200:203], v243 offset:6144
	ds_read_b128 v[204:207], v243 offset:7168
	global_load_lds_dwordx4 v[220:221], off
	v_lshl_add_u64 v[220:221], s[46:47], 0, v[142:143]
	s_add_i32 m0, s6, 0xe000
	s_nop 0
	global_load_lds_dwordx4 v[220:221], off
	s_waitcnt vmcnt(8)
	s_waitcnt lgkmcnt(0)
	s_barrier
	s_waitcnt lgkmcnt(0)
	v_mfma_f32_16x16x32_bf16 v[122:125], v[144:147], v[176:179], v[122:125]
	v_mfma_f32_16x16x32_bf16 v[126:129], v[152:155], v[176:179], v[126:129]
	v_mfma_f32_16x16x32_bf16 v[30:33], v[144:147], v[184:187], v[30:33]
	v_mfma_f32_16x16x32_bf16 v[26:29], v[152:155], v[184:187], v[26:29]
	v_mfma_f32_16x16x32_bf16 v[14:17], v[144:147], v[192:195], v[14:17]
	v_mfma_f32_16x16x32_bf16 v[10:13], v[152:155], v[192:195], v[10:13]
	v_mfma_f32_16x16x32_bf16 v[110:113], v[144:147], v[200:203], v[110:113]
	v_mfma_f32_16x16x32_bf16 v[106:109], v[152:155], v[200:203], v[106:109]
	v_mfma_f32_16x16x32_bf16 v[122:125], v[148:151], v[180:183], v[122:125]
	v_mfma_f32_16x16x32_bf16 v[126:129], v[156:159], v[180:183], v[126:129]
	v_mfma_f32_16x16x32_bf16 v[30:33], v[148:151], v[188:191], v[30:33]
	v_mfma_f32_16x16x32_bf16 v[26:29], v[156:159], v[188:191], v[26:29]
	v_mfma_f32_16x16x32_bf16 v[14:17], v[148:151], v[196:199], v[14:17]
	v_mfma_f32_16x16x32_bf16 v[10:13], v[156:159], v[196:199], v[10:13]
	v_mfma_f32_16x16x32_bf16 v[110:113], v[148:151], v[204:207], v[110:113]
	v_mfma_f32_16x16x32_bf16 v[106:109], v[156:159], v[204:207], v[106:109]
	v_mfma_f32_16x16x32_bf16 v[118:121], v[160:163], v[176:179], v[118:121]
	v_mfma_f32_16x16x32_bf16 v[114:117], v[168:171], v[176:179], v[114:117]
	v_mfma_f32_16x16x32_bf16 v[22:25], v[160:163], v[184:187], v[22:25]
	v_mfma_f32_16x16x32_bf16 v[18:21], v[168:171], v[184:187], v[18:21]
	v_mfma_f32_16x16x32_bf16 v[6:9], v[160:163], v[192:195], v[6:9]
	v_mfma_f32_16x16x32_bf16 v[2:5], v[168:171], v[192:195], v[2:5]
	v_mfma_f32_16x16x32_bf16 v[102:105], v[160:163], v[200:203], v[102:105]
	v_mfma_f32_16x16x32_bf16 v[98:101], v[168:171], v[200:203], v[98:101]
	v_mfma_f32_16x16x32_bf16 v[118:121], v[164:167], v[180:183], v[118:121]
	v_mfma_f32_16x16x32_bf16 v[114:117], v[172:175], v[180:183], v[114:117]
	v_mfma_f32_16x16x32_bf16 v[22:25], v[164:167], v[188:191], v[22:25]
	v_mfma_f32_16x16x32_bf16 v[18:21], v[172:175], v[188:191], v[18:21]
	v_mfma_f32_16x16x32_bf16 v[6:9], v[164:167], v[196:199], v[6:9]
	v_mfma_f32_16x16x32_bf16 v[2:5], v[172:175], v[196:199], v[2:5]
	v_mfma_f32_16x16x32_bf16 v[102:105], v[164:167], v[204:207], v[102:105]
	v_mfma_f32_16x16x32_bf16 v[98:101], v[172:175], v[204:207], v[98:101]
	s_barrier
; #define PG8_STAGE(bufoff, gbase, voff) do { _Pragma("unroll") for (int _i = 0; _i < 2; ++_i) \
;         __builtin_amdgcn_global_load_lds((const unsigned*)((const char*)(gbase) + (voff)[_i]), (LAS unsigned*)(lds + (bufoff) + ldsw + _i * 8192), 16, 0, 0); } while (0)
; #define PG8_LDA(dst, b, h) do { _Pragma("unroll") for (int m = 0; m < 4; ++m) _Pragma("unroll") for (int k = 0; k < 2; ++k) dst[m][k] = *(const LAS bf16x8*)(lds + PG8_SA(b, h) + aoff + m * 2048 + k * 1024); } while (0)
; #define PG8_LDB(dst, b, h) do { _Pragma("unroll") for (int n = 0; n < 2; ++n) _Pragma("unroll") for (int k = 0; k < 2; ++k) dst[n][k] = *(const LAS bf16x8*)(lds + PG8_SB(b, h) + boff + n * 2048 + k * 1024); } while (0)
; #define PG8_MMA(ai, bj, At, Bt) do { __builtin_amdgcn_s_setprio(1); _Pragma("unroll") for (int m = 0; m < 4; ++m) _Pragma("unroll") for (int n = 0; n < 2; ++n) _Pragma("unroll") for (int k = 0; k < 2; ++k) \
;         acc[ai][bj][m][n] = __builtin_amdgcn_mfma_f32_16x16x32_bf16(Bt[n][k], At[m][k], acc[ai][bj][m][n], 0, 0, 0); __builtin_amdgcn_s_setprio(0); } while (0)
; #define PG8_WAIT_V(n) asm volatile("s_waitcnt vmcnt(" #n ")" ::: "memory")
; #define PG8_WAIT_L(n) asm volatile("s_waitcnt lgkmcnt(" #n ")" ::: "memory")
; #define PG8_BAR __builtin_amdgcn_s_barrier()
; #define PG8_SCHED __builtin_amdgcn_sched_barrier(0)
; template <class Epi>
; __device__ __forceinline__ void gemm_phase(LAS unsigned char* lds, const Gemm g, const Epi& E) {
;     ...
;             PG8_LDA(At, 0, 1); PG8_STAGE(PG8_SB(0, 0), b2, voffB); PG8_STAGE(PG8_SB(0, 1), b2 + hstepB, voffB); PG8_STAGE(PG8_SA(0, 0), a2, voffA);
;             PG8_WAIT_V(8); PG8_WAIT_L(0); PG8_BAR; PG8_MMA(1, 0, At, B0); PG8_MMA(1, 1, At, B1); PG8_BAR; PG8_SCHED;
;             PG8_LDB(B0, 1, 0); PG8_LDB(B1, 1, 1); PG8_SCHED; PG8_LDA(At, 1, 0); PG8_STAGE(PG8_SA(0, 1), a2 + hstepA, voffA);
	s_add_i32 vcc_lo, vcc_lo, s55
	v_lshl_add_u64 v[220:221], s[52:53], 0, v[0:1]
	s_mov_b32 m0, vcc_lo
	ds_read_b128 v[176:179], v243 offset:16384
	ds_read_b128 v[180:183], v243 offset:17408
	ds_read_b128 v[184:187], v243 offset:18432
	ds_read_b128 v[188:191], v243 offset:19456
	ds_read_b128 v[192:195], v243 offset:20480
	ds_read_b128 v[196:199], v243 offset:21504
	ds_read_b128 v[200:203], v243 offset:22528
	ds_read_b128 v[204:207], v243 offset:23552
	global_load_lds_dwordx4 v[220:221], off
	s_add_i32 m0, vcc_lo, 0x2000
	v_lshl_add_u64 v[222:223], s[52:53], 0, v[130:131]
	s_add_u32 s52, s52, s80
	s_addc_u32 s53, s53, s81
	s_add_i32 s51, s51, s55
	global_load_lds_dwordx4 v[222:223], off
	v_lshl_add_u64 v[224:225], s[52:53], 0, v[0:1]
	s_mov_b32 m0, s51
	v_lshl_add_u64 v[226:227], s[52:53], 0, v[130:131]
	global_load_lds_dwordx4 v[224:225], off
	s_add_i32 m0, s51, 0x2000
	v_lshl_add_u64 v[228:229], s[48:49], 0, v[134:135]
	global_load_lds_dwordx4 v[226:227], off
	s_mov_b32 m0, s6
	v_lshl_add_u64 v[230:231], s[48:49], 0, v[132:133]
	global_load_lds_dwordx4 v[228:229], off
	s_mov_b32 m0, s7
	s_nop 0
	global_load_lds_dwordx4 v[230:231], off
	s_waitcnt vmcnt(8)
	s_waitcnt lgkmcnt(0)
	s_barrier
	s_waitcnt lgkmcnt(0)
	v_mfma_f32_16x16x32_bf16 v[94:97], v[144:147], v[176:179], v[94:97]
	v_mfma_f32_16x16x32_bf16 v[90:93], v[152:155], v[176:179], v[90:93]
	v_mfma_f32_16x16x32_bf16 v[62:65], v[144:147], v[184:187], v[62:65]
	v_mfma_f32_16x16x32_bf16 v[58:61], v[152:155], v[184:187], v[58:61]
	v_mfma_f32_16x16x32_bf16 v[46:49], v[144:147], v[192:195], v[46:49]
	v_mfma_f32_16x16x32_bf16 v[42:45], v[152:155], v[192:195], v[42:45]
	v_mfma_f32_16x16x32_bf16 v[78:81], v[144:147], v[200:203], v[78:81]
	v_mfma_f32_16x16x32_bf16 v[74:77], v[152:155], v[200:203], v[74:77]
	v_mfma_f32_16x16x32_bf16 v[94:97], v[148:151], v[180:183], v[94:97]
	v_mfma_f32_16x16x32_bf16 v[90:93], v[156:159], v[180:183], v[90:93]
	v_mfma_f32_16x16x32_bf16 v[62:65], v[148:151], v[188:191], v[62:65]
	v_mfma_f32_16x16x32_bf16 v[58:61], v[156:159], v[188:191], v[58:61]
	v_mfma_f32_16x16x32_bf16 v[46:49], v[148:151], v[196:199], v[46:49]
	v_mfma_f32_16x16x32_bf16 v[42:45], v[156:159], v[196:199], v[42:45]
	v_mfma_f32_16x16x32_bf16 v[78:81], v[148:151], v[204:207], v[78:81]
	v_mfma_f32_16x16x32_bf16 v[74:77], v[156:159], v[204:207], v[74:77]
	v_mfma_f32_16x16x32_bf16 v[86:89], v[160:163], v[176:179], v[86:89]
	v_mfma_f32_16x16x32_bf16 v[82:85], v[168:171], v[176:179], v[82:85]
	v_mfma_f32_16x16x32_bf16 v[54:57], v[160:163], v[184:187], v[54:57]
	v_mfma_f32_16x16x32_bf16 v[50:53], v[168:171], v[184:187], v[50:53]
	v_mfma_f32_16x16x32_bf16 v[38:41], v[160:163], v[192:195], v[38:41]
	v_mfma_f32_16x16x32_bf16 v[34:37], v[168:171], v[192:195], v[34:37]
	v_mfma_f32_16x16x32_bf16 v[70:73], v[160:163], v[200:203], v[70:73]
	v_mfma_f32_16x16x32_bf16 v[66:69], v[168:171], v[200:203], v[66:69]
	v_mfma_f32_16x16x32_bf16 v[86:89], v[164:167], v[180:183], v[86:89]
	v_mfma_f32_16x16x32_bf16 v[82:85], v[172:175], v[180:183], v[82:85]
	v_mfma_f32_16x16x32_bf16 v[54:57], v[164:167], v[188:191], v[54:57]
	v_mfma_f32_16x16x32_bf16 v[50:53], v[172:175], v[188:191], v[50:53]
	v_mfma_f32_16x16x32_bf16 v[38:41], v[164:167], v[196:199], v[38:41]
	v_mfma_f32_16x16x32_bf16 v[34:37], v[172:175], v[196:199], v[34:37]
	v_mfma_f32_16x16x32_bf16 v[70:73], v[164:167], v[204:207], v[70:73]
	v_mfma_f32_16x16x32_bf16 v[66:69], v[172:175], v[204:207], v[66:69]
	s_barrier
	s_add_i32 s51, 0, 0x18000
	s_add_i32 s52, 0, 0x1c000
	v_add_u32_e32 v156, s51, v241
	v_add_u32_e32 v172, s52, v241
	ds_read_b128 v[144:147], v156
	ds_read_b128 v[148:151], v156 offset:1024
	ds_read_b128 v[152:155], v156 offset:2048
	ds_read_b128 v[156:159], v156 offset:3072
	ds_read_b128 v[160:163], v172
	ds_read_b128 v[164:167], v172 offset:1024
	ds_read_b128 v[168:171], v172 offset:2048
	ds_read_b128 v[172:175], v172 offset:3072
	s_add_u32 s48, s48, s74
	s_addc_u32 s49, s49, s75
	s_mov_b32 m0, s8
	v_lshl_add_u64 v[232:233], s[48:49], 0, v[134:135]
	ds_read_b128 v[176:179], v243 offset:32768
	ds_read_b128 v[180:183], v243 offset:33792
	ds_read_b128 v[184:187], v243 offset:34816
	ds_read_b128 v[188:191], v243 offset:35840
	ds_read_b128 v[192:195], v243 offset:36864
	ds_read_b128 v[196:199], v243 offset:37888
	ds_read_b128 v[200:203], v243 offset:38912
	ds_read_b128 v[204:207], v243 offset:39936
	global_load_lds_dwordx4 v[232:233], off
	v_lshl_add_u64 v[232:233], s[48:49], 0, v[132:133]
	s_mov_b32 m0, s9
	s_nop 0
	global_load_lds_dwordx4 v[232:233], off
	s_waitcnt vmcnt(8)
	s_waitcnt lgkmcnt(0)
	s_barrier
; #define PG8_STAGE(bufoff, gbase, voff) do { _Pragma("unroll") for (int _i = 0; _i < 2; ++_i) \
;         __builtin_amdgcn_global_load_lds((const unsigned*)((const char*)(gbase) + (voff)[_i]), (LAS unsigned*)(lds + (bufoff) + ldsw + _i * 8192), 16, 0, 0); } while (0)
; #define PG8_LDA(dst, b, h) do { _Pragma("unroll") for (int m = 0; m < 4; ++m) _Pragma("unroll") for (int k = 0; k < 2; ++k) dst[m][k] = *(const LAS bf16x8*)(lds + PG8_SA(b, h) + aoff + m * 2048 + k * 1024); } while (0)
; #define PG8_MMA(ai, bj, At, Bt) do { __builtin_amdgcn_s_setprio(1); _Pragma("unroll") for (int m = 0; m < 4; ++m) _Pragma("unroll") for (int n = 0; n < 2; ++n) _Pragma("unroll") for (int k = 0; k < 2; ++k) \
;         acc[ai][bj][m][n] = __builtin_amdgcn_mfma_f32_16x16x32_bf16(Bt[n][k], At[m][k], acc[ai][bj][m][n], 0, 0, 0); __builtin_amdgcn_s_setprio(0); } while (0)
; #define PG8_WAIT_V(n) asm volatile("s_waitcnt vmcnt(" #n ")" ::: "memory")
; #define PG8_WAIT_L(n) asm volatile("s_waitcnt lgkmcnt(" #n ")" ::: "memory")
; #define PG8_BAR __builtin_amdgcn_s_barrier()
; #define PG8_SCHED __builtin_amdgcn_sched_barrier(0)
; template <class Epi>
; __device__ __forceinline__ void gemm_phase(LAS unsigned char* lds, const Gemm g, const Epi& E) {
;     ...
;             PG8_WAIT_V(8); PG8_WAIT_L(0); PG8_BAR; PG8_MMA(0, 0, At, B0); PG8_MMA(0, 1, At, B1); PG8_BAR; PG8_SCHED;
;             PG8_LDA(At, 1, 1); PG8_STAGE(PG8_SB(1, 0), b3, voffB); PG8_STAGE(PG8_SB(1, 1), b3 + hstepB, voffB); PG8_STAGE(PG8_SA(1, 0), a3, voffA);
;             PG8_WAIT_V(8); PG8_WAIT_L(0); PG8_BAR; PG8_MMA(1, 0, At, B0); PG8_MMA(1, 1, At, B1); PG8_BAR; PG8_SCHED;
;         }
	s_waitcnt lgkmcnt(0)
	v_mfma_f32_16x16x32_bf16 v[122:125], v[144:147], v[176:179], v[122:125]
	v_mfma_f32_16x16x32_bf16 v[126:129], v[152:155], v[176:179], v[126:129]
	v_mfma_f32_16x16x32_bf16 v[30:33], v[144:147], v[184:187], v[30:33]
	v_mfma_f32_16x16x32_bf16 v[26:29], v[152:155], v[184:187], v[26:29]
	v_mfma_f32_16x16x32_bf16 v[14:17], v[144:147], v[192:195], v[14:17]
	v_mfma_f32_16x16x32_bf16 v[10:13], v[152:155], v[192:195], v[10:13]
	v_mfma_f32_16x16x32_bf16 v[110:113], v[144:147], v[200:203], v[110:113]
	v_mfma_f32_16x16x32_bf16 v[106:109], v[152:155], v[200:203], v[106:109]
	v_mfma_f32_16x16x32_bf16 v[122:125], v[148:151], v[180:183], v[122:125]
	v_mfma_f32_16x16x32_bf16 v[126:129], v[156:159], v[180:183], v[126:129]
	v_mfma_f32_16x16x32_bf16 v[30:33], v[148:151], v[188:191], v[30:33]
	v_mfma_f32_16x16x32_bf16 v[26:29], v[156:159], v[188:191], v[26:29]
	v_mfma_f32_16x16x32_bf16 v[14:17], v[148:151], v[196:199], v[14:17]
	v_mfma_f32_16x16x32_bf16 v[10:13], v[156:159], v[196:199], v[10:13]
	v_mfma_f32_16x16x32_bf16 v[110:113], v[148:151], v[204:207], v[110:113]
	v_mfma_f32_16x16x32_bf16 v[106:109], v[156:159], v[204:207], v[106:109]
	v_mfma_f32_16x16x32_bf16 v[118:121], v[160:163], v[176:179], v[118:121]
	v_mfma_f32_16x16x32_bf16 v[114:117], v[168:171], v[176:179], v[114:117]
	v_mfma_f32_16x16x32_bf16 v[22:25], v[160:163], v[184:187], v[22:25]
	v_mfma_f32_16x16x32_bf16 v[18:21], v[168:171], v[184:187], v[18:21]
	v_mfma_f32_16x16x32_bf16 v[6:9], v[160:163], v[192:195], v[6:9]
	v_mfma_f32_16x16x32_bf16 v[2:5], v[168:171], v[192:195], v[2:5]
	v_mfma_f32_16x16x32_bf16 v[102:105], v[160:163], v[200:203], v[102:105]
	v_mfma_f32_16x16x32_bf16 v[98:101], v[168:171], v[200:203], v[98:101]
	v_mfma_f32_16x16x32_bf16 v[118:121], v[164:167], v[180:183], v[118:121]
	v_mfma_f32_16x16x32_bf16 v[114:117], v[172:175], v[180:183], v[114:117]
	v_mfma_f32_16x16x32_bf16 v[22:25], v[164:167], v[188:191], v[22:25]
	v_mfma_f32_16x16x32_bf16 v[18:21], v[172:175], v[188:191], v[18:21]
	v_mfma_f32_16x16x32_bf16 v[6:9], v[164:167], v[196:199], v[6:9]
	v_mfma_f32_16x16x32_bf16 v[2:5], v[172:175], v[196:199], v[2:5]
	v_mfma_f32_16x16x32_bf16 v[102:105], v[164:167], v[204:207], v[102:105]
	v_mfma_f32_16x16x32_bf16 v[98:101], v[172:175], v[204:207], v[98:101]
	s_barrier
	s_add_i32 s48, s51, s55
	v_lshl_add_u64 v[220:221], v[220:221], 0, s[28:29]
	s_mov_b32 m0, s48
	ds_read_b128 v[176:179], v243 offset:49152
	ds_read_b128 v[180:183], v243 offset:50176
	ds_read_b128 v[184:187], v243 offset:51200
	ds_read_b128 v[188:191], v243 offset:52224
	ds_read_b128 v[192:195], v243 offset:53248
	ds_read_b128 v[196:199], v243 offset:54272
	ds_read_b128 v[200:203], v243 offset:55296
	ds_read_b128 v[204:207], v243 offset:56320
	global_load_lds_dwordx4 v[220:221], off
	v_lshl_add_u64 v[220:221], v[222:223], 0, s[28:29]
	s_add_i32 m0, s48, 0x2000
	s_add_i32 s48, s52, s55
	global_load_lds_dwordx4 v[220:221], off
	v_lshl_add_u64 v[220:221], v[224:225], 0, s[28:29]
	s_mov_b32 m0, s48
	s_nop 0
	global_load_lds_dwordx4 v[220:221], off
	v_lshl_add_u64 v[220:221], v[226:227], 0, s[28:29]
	s_add_i32 m0, s48, 0x2000
	s_nop 0
	global_load_lds_dwordx4 v[220:221], off
	v_lshl_add_u64 v[220:221], v[228:229], 0, s[28:29]
	s_mov_b32 m0, s61
	s_nop 0
	global_load_lds_dwordx4 v[220:221], off
	v_lshl_add_u64 v[220:221], v[230:231], 0, s[28:29]
	s_mov_b32 m0, s72
	s_nop 0
	global_load_lds_dwordx4 v[220:221], off
	s_waitcnt vmcnt(8)
	s_waitcnt lgkmcnt(0)
	s_barrier
	s_waitcnt lgkmcnt(0)
	v_mfma_f32_16x16x32_bf16 v[94:97], v[144:147], v[176:179], v[94:97]
	v_mfma_f32_16x16x32_bf16 v[90:93], v[152:155], v[176:179], v[90:93]
	v_mfma_f32_16x16x32_bf16 v[62:65], v[144:147], v[184:187], v[62:65]
	v_mfma_f32_16x16x32_bf16 v[58:61], v[152:155], v[184:187], v[58:61]
	v_mfma_f32_16x16x32_bf16 v[46:49], v[144:147], v[192:195], v[46:49]
	v_mfma_f32_16x16x32_bf16 v[42:45], v[152:155], v[192:195], v[42:45]
	v_mfma_f32_16x16x32_bf16 v[78:81], v[144:147], v[200:203], v[78:81]
	v_mfma_f32_16x16x32_bf16 v[74:77], v[152:155], v[200:203], v[74:77]
	v_mfma_f32_16x16x32_bf16 v[94:97], v[148:151], v[180:183], v[94:97]
	v_mfma_f32_16x16x32_bf16 v[90:93], v[156:159], v[180:183], v[90:93]
	v_mfma_f32_16x16x32_bf16 v[62:65], v[148:151], v[188:191], v[62:65]
	v_mfma_f32_16x16x32_bf16 v[58:61], v[156:159], v[188:191], v[58:61]
	v_mfma_f32_16x16x32_bf16 v[46:49], v[148:151], v[196:199], v[46:49]
	v_mfma_f32_16x16x32_bf16 v[42:45], v[156:159], v[196:199], v[42:45]
	v_mfma_f32_16x16x32_bf16 v[78:81], v[148:151], v[204:207], v[78:81]
	v_mfma_f32_16x16x32_bf16 v[74:77], v[156:159], v[204:207], v[74:77]
	v_mfma_f32_16x16x32_bf16 v[86:89], v[160:163], v[176:179], v[86:89]
	v_mfma_f32_16x16x32_bf16 v[82:85], v[168:171], v[176:179], v[82:85]
	v_mfma_f32_16x16x32_bf16 v[54:57], v[160:163], v[184:187], v[54:57]
	v_mfma_f32_16x16x32_bf16 v[50:53], v[168:171], v[184:187], v[50:53]
	v_mfma_f32_16x16x32_bf16 v[38:41], v[160:163], v[192:195], v[38:41]
	v_mfma_f32_16x16x32_bf16 v[34:37], v[168:171], v[192:195], v[34:37]
	v_mfma_f32_16x16x32_bf16 v[70:73], v[160:163], v[200:203], v[70:73]
	v_mfma_f32_16x16x32_bf16 v[66:69], v[168:171], v[200:203], v[66:69]
	v_mfma_f32_16x16x32_bf16 v[86:89], v[164:167], v[180:183], v[86:89]
	v_mfma_f32_16x16x32_bf16 v[82:85], v[172:175], v[180:183], v[82:85]
	v_mfma_f32_16x16x32_bf16 v[54:57], v[164:167], v[188:191], v[54:57]
	v_mfma_f32_16x16x32_bf16 v[50:53], v[172:175], v[188:191], v[50:53]
	v_mfma_f32_16x16x32_bf16 v[38:41], v[164:167], v[196:199], v[38:41]
	v_mfma_f32_16x16x32_bf16 v[34:37], v[172:175], v[196:199], v[34:37]
	v_mfma_f32_16x16x32_bf16 v[70:73], v[164:167], v[204:207], v[70:73]
	v_mfma_f32_16x16x32_bf16 v[66:69], v[172:175], v[204:207], v[66:69]
	s_barrier
	s_add_u32 s46, s46, 0x100
	s_addc_u32 s47, s47, 0
	s_add_u32 s24, s24, 0x100
	s_addc_u32 s25, s25, 0
	s_cmp_ge_i32 s50, s18
	s_mov_b32 s48, s50
	s_cbranch_scc0 .LBB0_792
	s_setprio 0

; #define PG8_STAGE(bufoff, gbase, voff) do { _Pragma("unroll") for (int _i = 0; _i < 2; ++_i) \
;         __builtin_amdgcn_global_load_lds((const unsigned*)((const char*)(gbase) + (voff)[_i]), (LAS unsigned*)(lds + (bufoff) + ldsw + _i * 8192), 16, 0, 0); } while (0)
; #define PG8_LDA(dst, b, h) do { _Pragma("unroll") for (int m = 0; m < 4; ++m) _Pragma("unroll") for (int k = 0; k < 2; ++k) dst[m][k] = *(const LAS bf16x8*)(lds + PG8_SA(b, h) + aoff + m * 2048 + k * 1024); } while (0)
; #define PG8_LDB(dst, b, h) do { _Pragma("unroll") for (int n = 0; n < 2; ++n) _Pragma("unroll") for (int k = 0; k < 2; ++k) dst[n][k] = *(const LAS bf16x8*)(lds + PG8_SB(b, h) + boff + n * 2048 + k * 1024); } while (0)
; #define PG8_MMA(ai, bj, At, Bt) do { __builtin_amdgcn_s_setprio(1); _Pragma("unroll") for (int m = 0; m < 4; ++m) _Pragma("unroll") for (int n = 0; n < 2; ++n) _Pragma("unroll") for (int k = 0; k < 2; ++k) \
;         acc[ai][bj][m][n] = __builtin_amdgcn_mfma_f32_16x16x32_bf16(Bt[n][k], At[m][k], acc[ai][bj][m][n], 0, 0, 0); __builtin_amdgcn_s_setprio(0); } while (0)
; #define PG8_WAIT_V(n) asm volatile("s_waitcnt vmcnt(" #n ")" ::: "memory")
; #define PG8_WAIT_L(n) asm volatile("s_waitcnt lgkmcnt(" #n ")" ::: "memory")
; #define PG8_BAR __builtin_amdgcn_s_barrier()
; #define PG8_SCHED __builtin_amdgcn_sched_barrier(0)
; template <class Epi>
; __device__ __forceinline__ void gemm_phase(LAS unsigned char* lds, const Gemm g, const Epi& E) {
;     ...
;             const bool last = (t == nt - 2);
;             const char* a1 = cA + (size_t)(t + 1) * kstep;
;             const char* a2 = last ? nA : cA + (size_t)(t + 2) * kstep; const char* b2 = last ? nB : cB + (size_t)(t + 2) * kstep;
;             const char* a3 = a2 + kstep; const char* b3 = b2 + kstep;
;             PG8_LDB(B0, 0, 0); PG8_LDB(B1, 0, 1); PG8_SCHED; PG8_LDA(At, 0, 0); PG8_STAGE(PG8_SA(1, 1), a1 + hstepA, voffA);
;             PG8_WAIT_V(8); PG8_WAIT_L(0); PG8_BAR; PG8_MMA(0, 0, At, B0); PG8_MMA(0, 1, At, B1); PG8_BAR; PG8_SCHED;
;     ...
;         if (!has_next) break;
; #pragma unroll
;         for (int a = 0; a < 2; ++a)
; #pragma unroll
;             for (int b = 0; b < 2; ++b)
; #pragma unroll
;                 for (int m = 0; m < 4; ++m)
; #pragma unroll
;                     for (int n = 0; n < 2; ++n) acc[a][b][m][n] = (f32x4){0.f, 0.f, 0.f, 0.f};
;         cur = nxt; cA = nA; cB = nB; ++ui;
.LBB0_934:
	s_andn2_b64 vcc, exec, s[46:47]
	s_waitcnt lgkmcnt(0)
	s_cbranch_vccnz .LBB0_937
	s_add_u32 s58, s58, 0x80
	s_addc_u32 s59, s59, 0
	s_add_u32 s20, s62, 0x100
	s_addc_u32 s21, s63, 0
	s_mov_b32 s62, 0
	v_mov_b64_e32 v[2:3], 0
	v_mov_b64_e32 v[4:5], 0
	v_mov_b64_e32 v[6:7], 0
	v_mov_b64_e32 v[8:9], 0
	v_mov_b64_e32 v[10:11], 0
	v_mov_b64_e32 v[12:13], 0
	v_mov_b64_e32 v[14:15], 0
	v_mov_b64_e32 v[16:17], 0
	v_mov_b64_e32 v[18:19], 0
	v_mov_b64_e32 v[20:21], 0
	v_mov_b64_e32 v[22:23], 0
	v_mov_b64_e32 v[24:25], 0
	v_mov_b64_e32 v[26:27], 0
	v_mov_b64_e32 v[28:29], 0
	v_mov_b64_e32 v[30:31], 0
	v_mov_b64_e32 v[32:33], 0
	v_mov_b64_e32 v[34:35], 0
	v_mov_b64_e32 v[36:37], 0
	v_mov_b64_e32 v[38:39], 0
	v_mov_b64_e32 v[40:41], 0
	v_mov_b64_e32 v[42:43], 0
	v_mov_b64_e32 v[44:45], 0
	v_mov_b64_e32 v[46:47], 0
	v_mov_b64_e32 v[48:49], 0
	v_mov_b64_e32 v[50:51], 0
	v_mov_b64_e32 v[52:53], 0
	v_mov_b64_e32 v[54:55], 0
	v_mov_b64_e32 v[56:57], 0
	v_mov_b64_e32 v[58:59], 0
	v_mov_b64_e32 v[60:61], 0
	v_mov_b64_e32 v[62:63], 0
	v_mov_b64_e32 v[64:65], 0
	v_mov_b64_e32 v[66:67], 0
	v_mov_b64_e32 v[68:69], 0
	v_mov_b64_e32 v[70:71], 0
	v_mov_b64_e32 v[72:73], 0
	v_mov_b64_e32 v[74:75], 0
	v_mov_b64_e32 v[76:77], 0
	v_mov_b64_e32 v[78:79], 0
	v_mov_b64_e32 v[80:81], 0
	v_mov_b64_e32 v[82:83], 0
	v_mov_b64_e32 v[84:85], 0
	v_mov_b64_e32 v[86:87], 0
	v_mov_b64_e32 v[88:89], 0
	v_mov_b64_e32 v[90:91], 0
	v_mov_b64_e32 v[92:93], 0
	v_mov_b64_e32 v[94:95], 0
	v_mov_b64_e32 v[96:97], 0
	v_mov_b64_e32 v[98:99], 0
	v_mov_b64_e32 v[100:101], 0
	v_mov_b64_e32 v[102:103], 0
	v_mov_b64_e32 v[104:105], 0
	v_mov_b64_e32 v[106:107], 0
	v_mov_b64_e32 v[108:109], 0
	v_mov_b64_e32 v[110:111], 0
	v_mov_b64_e32 v[112:113], 0
	v_mov_b64_e32 v[114:115], 0
	v_mov_b64_e32 v[116:117], 0
	v_mov_b64_e32 v[118:119], 0
	v_mov_b64_e32 v[120:121], 0
	v_mov_b64_e32 v[122:123], 0
	v_mov_b64_e32 v[124:125], 0
	v_mov_b64_e32 v[126:127], 0
	v_mov_b64_e32 v[128:129], 0
	s_and_b64 vcc, exec, s[48:49]
	s_cbranch_vccnz .Lg936_prio_skip
	s_setprio 1
.Lg936_prio_skip:
.LBB0_936:
	s_add_i32 s70, s62, 2
	s_add_u32 s71, s58, 0x80
	s_addc_u32 s63, s59, 0
	s_add_i32 s72, 0, 0x10000
	s_cmp_eq_u32 s35, s62
	s_cselect_b32 s63, s45, s63
	s_cselect_b32 s62, s44, s71
	v_add_u32_e32 v144, s72, v147
	s_cselect_b32 s75, s53, s21
	s_cselect_b32 s74, s52, s20
	s_add_i32 s71, 0, 0x14000
	ds_read_b128 v[140:143], v144
	ds_read_b128 v[154:157], v144 offset:1024
	ds_read_b128 v[158:161], v144 offset:2048
	ds_read_b128 v[162:165], v144 offset:3072
	v_add_u32_e32 v144, s71, v147
	ds_read_b128 v[166:169], v144
	ds_read_b128 v[170:173], v144 offset:1024
	ds_read_b128 v[174:177], v144 offset:2048
	ds_read_b128 v[178:181], v144 offset:3072
	v_lshl_add_u64 v[144:145], s[58:59], 0, v[136:137]
	s_add_i32 m0, s7, 0xc000
	ds_read_b128 v[182:185], v151
	ds_read_b128 v[186:189], v151 offset:1024
	ds_read_b128 v[190:193], v151 offset:2048
	ds_read_b128 v[194:197], v151 offset:3072
	ds_read_b128 v[198:201], v151 offset:4096
	ds_read_b128 v[202:205], v151 offset:5120
	ds_read_b128 v[224:227], v151 offset:6144
	ds_read_b128 v[228:231], v151 offset:7168
	global_load_lds_dwordx4 v[144:145], off
	v_lshl_add_u64 v[144:145], s[58:59], 0, v[138:139]
	s_add_i32 m0, s7, 0xe000
	s_nop 0
	global_load_lds_dwordx4 v[144:145], off
	s_waitcnt vmcnt(8)
	s_waitcnt lgkmcnt(0)
	s_barrier
	s_waitcnt lgkmcnt(0)
	v_mfma_f32_16x16x32_bf16 v[126:129], v[140:143], v[182:185], v[126:129]
	v_mfma_f32_16x16x32_bf16 v[122:125], v[158:161], v[182:185], v[122:125]
	v_mfma_f32_16x16x32_bf16 v[110:113], v[140:143], v[190:193], v[110:113]
	v_mfma_f32_16x16x32_bf16 v[106:109], v[158:161], v[190:193], v[106:109]
	v_mfma_f32_16x16x32_bf16 v[94:97], v[140:143], v[198:201], v[94:97]
	v_mfma_f32_16x16x32_bf16 v[90:93], v[158:161], v[198:201], v[90:93]
	v_mfma_f32_16x16x32_bf16 v[78:81], v[140:143], v[224:227], v[78:81]
	v_mfma_f32_16x16x32_bf16 v[74:77], v[158:161], v[224:227], v[74:77]
	v_mfma_f32_16x16x32_bf16 v[126:129], v[154:157], v[186:189], v[126:129]
	v_mfma_f32_16x16x32_bf16 v[122:125], v[162:165], v[186:189], v[122:125]
	v_mfma_f32_16x16x32_bf16 v[110:113], v[154:157], v[194:197], v[110:113]
	v_mfma_f32_16x16x32_bf16 v[106:109], v[162:165], v[194:197], v[106:109]
	v_mfma_f32_16x16x32_bf16 v[94:97], v[154:157], v[202:205], v[94:97]
	v_mfma_f32_16x16x32_bf16 v[90:93], v[162:165], v[202:205], v[90:93]
	v_mfma_f32_16x16x32_bf16 v[78:81], v[154:157], v[228:231], v[78:81]
	v_mfma_f32_16x16x32_bf16 v[74:77], v[162:165], v[228:231], v[74:77]
	v_mfma_f32_16x16x32_bf16 v[118:121], v[166:169], v[182:185], v[118:121]
	v_mfma_f32_16x16x32_bf16 v[114:117], v[174:177], v[182:185], v[114:117]
	v_mfma_f32_16x16x32_bf16 v[102:105], v[166:169], v[190:193], v[102:105]
	v_mfma_f32_16x16x32_bf16 v[98:101], v[174:177], v[190:193], v[98:101]
	v_mfma_f32_16x16x32_bf16 v[86:89], v[166:169], v[198:201], v[86:89]
	v_mfma_f32_16x16x32_bf16 v[82:85], v[174:177], v[198:201], v[82:85]
	v_mfma_f32_16x16x32_bf16 v[70:73], v[166:169], v[224:227], v[70:73]
	v_mfma_f32_16x16x32_bf16 v[66:69], v[174:177], v[224:227], v[66:69]
	v_mfma_f32_16x16x32_bf16 v[118:121], v[170:173], v[186:189], v[118:121]
	v_mfma_f32_16x16x32_bf16 v[114:117], v[178:181], v[186:189], v[114:117]
	v_mfma_f32_16x16x32_bf16 v[102:105], v[170:173], v[194:197], v[102:105]
	v_mfma_f32_16x16x32_bf16 v[98:101], v[178:181], v[194:197], v[98:101]
	v_mfma_f32_16x16x32_bf16 v[86:89], v[170:173], v[202:205], v[86:89]
	v_mfma_f32_16x16x32_bf16 v[82:85], v[178:181], v[202:205], v[82:85]
	v_mfma_f32_16x16x32_bf16 v[70:73], v[170:173], v[228:231], v[70:73]
	v_mfma_f32_16x16x32_bf16 v[66:69], v[178:181], v[228:231], v[66:69]
	s_barrier
; #define PG8_STAGE(bufoff, gbase, voff) do { _Pragma("unroll") for (int _i = 0; _i < 2; ++_i) \
;         __builtin_amdgcn_global_load_lds((const unsigned*)((const char*)(gbase) + (voff)[_i]), (LAS unsigned*)(lds + (bufoff) + ldsw + _i * 8192), 16, 0, 0); } while (0)
; #define PG8_LDA(dst, b, h) do { _Pragma("unroll") for (int m = 0; m < 4; ++m) _Pragma("unroll") for (int k = 0; k < 2; ++k) dst[m][k] = *(const LAS bf16x8*)(lds + PG8_SA(b, h) + aoff + m * 2048 + k * 1024); } while (0)
; #define PG8_LDB(dst, b, h) do { _Pragma("unroll") for (int n = 0; n < 2; ++n) _Pragma("unroll") for (int k = 0; k < 2; ++k) dst[n][k] = *(const LAS bf16x8*)(lds + PG8_SB(b, h) + boff + n * 2048 + k * 1024); } while (0)
; #define PG8_MMA(ai, bj, At, Bt) do { __builtin_amdgcn_s_setprio(1); _Pragma("unroll") for (int m = 0; m < 4; ++m) _Pragma("unroll") for (int n = 0; n < 2; ++n) _Pragma("unroll") for (int k = 0; k < 2; ++k) \
;         acc[ai][bj][m][n] = __builtin_amdgcn_mfma_f32_16x16x32_bf16(Bt[n][k], At[m][k], acc[ai][bj][m][n], 0, 0, 0); __builtin_amdgcn_s_setprio(0); } while (0)
; #define PG8_WAIT_V(n) asm volatile("s_waitcnt vmcnt(" #n ")" ::: "memory")
; #define PG8_WAIT_L(n) asm volatile("s_waitcnt lgkmcnt(" #n ")" ::: "memory")
; #define PG8_BAR __builtin_amdgcn_s_barrier()
; #define PG8_SCHED __builtin_amdgcn_sched_barrier(0)
; template <class Epi>
; __device__ __forceinline__ void gemm_phase(LAS unsigned char* lds, const Gemm g, const Epi& E) {
;     ...
;             PG8_LDA(At, 0, 1); PG8_STAGE(PG8_SB(0, 0), b2, voffB); PG8_STAGE(PG8_SB(0, 1), b2 + hstepB, voffB); PG8_STAGE(PG8_SA(0, 0), a2, voffA);
;             PG8_WAIT_V(8); PG8_WAIT_L(0); PG8_BAR; PG8_MMA(1, 0, At, B0); PG8_MMA(1, 1, At, B1); PG8_BAR; PG8_SCHED;
;             PG8_LDB(B0, 1, 0); PG8_LDB(B1, 1, 1); PG8_SCHED; PG8_LDA(At, 1, 0); PG8_STAGE(PG8_SA(0, 1), a2 + hstepA, voffA);
	s_add_i32 s72, s72, s6
	v_lshl_add_u64 v[144:145], s[74:75], 0, v[0:1]
	s_mov_b32 m0, s72
	ds_read_b128 v[182:185], v151 offset:16384
	ds_read_b128 v[186:189], v151 offset:17408
	ds_read_b128 v[190:193], v151 offset:18432
	ds_read_b128 v[194:197], v151 offset:19456
	ds_read_b128 v[198:201], v151 offset:20480
	ds_read_b128 v[202:205], v151 offset:21504
	ds_read_b128 v[224:227], v151 offset:22528
	ds_read_b128 v[228:231], v151 offset:23552
	global_load_lds_dwordx4 v[144:145], off
	s_add_i32 m0, s72, 0x2000
	v_lshl_add_u64 v[206:207], s[74:75], 0, v[130:131]
	s_add_u32 s74, s74, s10
	s_addc_u32 s75, s75, s11
	s_add_i32 s71, s71, s6
	global_load_lds_dwordx4 v[206:207], off
	v_lshl_add_u64 v[220:221], s[74:75], 0, v[0:1]
	s_mov_b32 m0, s71
	v_lshl_add_u64 v[222:223], s[74:75], 0, v[130:131]
	global_load_lds_dwordx4 v[220:221], off
	s_add_i32 m0, s71, 0x2000
	v_lshl_add_u64 v[232:233], s[62:63], 0, v[134:135]
	global_load_lds_dwordx4 v[222:223], off
	s_mov_b32 m0, s7
	v_lshl_add_u64 v[242:243], s[62:63], 0, v[132:133]
	global_load_lds_dwordx4 v[232:233], off
	s_mov_b32 m0, s8
	s_nop 0
	global_load_lds_dwordx4 v[242:243], off
	s_waitcnt vmcnt(8)
	s_waitcnt lgkmcnt(0)
	s_barrier
	s_waitcnt lgkmcnt(0)
	v_mfma_f32_16x16x32_bf16 v[62:65], v[140:143], v[182:185], v[62:65]
	v_mfma_f32_16x16x32_bf16 v[58:61], v[158:161], v[182:185], v[58:61]
	v_mfma_f32_16x16x32_bf16 v[46:49], v[140:143], v[190:193], v[46:49]
	v_mfma_f32_16x16x32_bf16 v[42:45], v[158:161], v[190:193], v[42:45]
	v_mfma_f32_16x16x32_bf16 v[30:33], v[140:143], v[198:201], v[30:33]
	v_mfma_f32_16x16x32_bf16 v[26:29], v[158:161], v[198:201], v[26:29]
	v_mfma_f32_16x16x32_bf16 v[14:17], v[140:143], v[224:227], v[14:17]
	v_mfma_f32_16x16x32_bf16 v[10:13], v[158:161], v[224:227], v[10:13]
	v_mfma_f32_16x16x32_bf16 v[62:65], v[154:157], v[186:189], v[62:65]
	v_mfma_f32_16x16x32_bf16 v[58:61], v[162:165], v[186:189], v[58:61]
	v_mfma_f32_16x16x32_bf16 v[46:49], v[154:157], v[194:197], v[46:49]
	v_mfma_f32_16x16x32_bf16 v[42:45], v[162:165], v[194:197], v[42:45]
	v_mfma_f32_16x16x32_bf16 v[30:33], v[154:157], v[202:205], v[30:33]
	v_mfma_f32_16x16x32_bf16 v[26:29], v[162:165], v[202:205], v[26:29]
	v_mfma_f32_16x16x32_bf16 v[14:17], v[154:157], v[228:231], v[14:17]
	v_mfma_f32_16x16x32_bf16 v[10:13], v[162:165], v[228:231], v[10:13]
	v_mfma_f32_16x16x32_bf16 v[54:57], v[166:169], v[182:185], v[54:57]
	v_mfma_f32_16x16x32_bf16 v[50:53], v[174:177], v[182:185], v[50:53]
	v_mfma_f32_16x16x32_bf16 v[38:41], v[166:169], v[190:193], v[38:41]
	v_mfma_f32_16x16x32_bf16 v[34:37], v[174:177], v[190:193], v[34:37]
	v_mfma_f32_16x16x32_bf16 v[22:25], v[166:169], v[198:201], v[22:25]
	v_mfma_f32_16x16x32_bf16 v[18:21], v[174:177], v[198:201], v[18:21]
	v_mfma_f32_16x16x32_bf16 v[6:9], v[166:169], v[224:227], v[6:9]
	v_mfma_f32_16x16x32_bf16 v[2:5], v[174:177], v[224:227], v[2:5]
	v_mfma_f32_16x16x32_bf16 v[54:57], v[170:173], v[186:189], v[54:57]
	v_mfma_f32_16x16x32_bf16 v[50:53], v[178:181], v[186:189], v[50:53]
	v_mfma_f32_16x16x32_bf16 v[38:41], v[170:173], v[194:197], v[38:41]
	v_mfma_f32_16x16x32_bf16 v[34:37], v[178:181], v[194:197], v[34:37]
	v_mfma_f32_16x16x32_bf16 v[22:25], v[170:173], v[202:205], v[22:25]
	v_mfma_f32_16x16x32_bf16 v[18:21], v[178:181], v[202:205], v[18:21]
	v_mfma_f32_16x16x32_bf16 v[6:9], v[170:173], v[228:231], v[6:9]
	v_mfma_f32_16x16x32_bf16 v[2:5], v[178:181], v[228:231], v[2:5]
	s_barrier
	s_add_i32 s71, 0, 0x18000
	v_add_u32_e32 v153, s71, v147
	s_add_i32 s72, 0, 0x1c000
	ds_read_b128 v[140:143], v153
	ds_read_b128 v[154:157], v153 offset:1024
	ds_read_b128 v[158:161], v153 offset:2048
	ds_read_b128 v[162:165], v153 offset:3072
	v_add_u32_e32 v153, s72, v147
	ds_read_b128 v[166:169], v153
	ds_read_b128 v[170:173], v153 offset:1024
	ds_read_b128 v[174:177], v153 offset:2048
	ds_read_b128 v[178:181], v153 offset:3072
	s_add_u32 s62, s62, s0
	s_addc_u32 s63, s63, s1
	s_mov_b32 m0, s9
	v_lshl_add_u64 v[244:245], s[62:63], 0, v[134:135]
	ds_read_b128 v[182:185], v151 offset:32768
	ds_read_b128 v[186:189], v151 offset:33792
	ds_read_b128 v[190:193], v151 offset:34816
	ds_read_b128 v[194:197], v151 offset:35840
	ds_read_b128 v[198:201], v151 offset:36864
	ds_read_b128 v[202:205], v151 offset:37888
	ds_read_b128 v[224:227], v151 offset:38912
	ds_read_b128 v[228:231], v151 offset:39936
	global_load_lds_dwordx4 v[244:245], off
	v_lshl_add_u64 v[244:245], s[62:63], 0, v[132:133]
	s_mov_b32 m0, s18
	s_nop 0
	global_load_lds_dwordx4 v[244:245], off
	s_waitcnt vmcnt(8)
	s_waitcnt lgkmcnt(0)
	s_barrier
; #define PG8_STAGE(bufoff, gbase, voff) do { _Pragma("unroll") for (int _i = 0; _i < 2; ++_i) \
;         __builtin_amdgcn_global_load_lds((const unsigned*)((const char*)(gbase) + (voff)[_i]), (LAS unsigned*)(lds + (bufoff) + ldsw + _i * 8192), 16, 0, 0); } while (0)
; #define PG8_LDA(dst, b, h) do { _Pragma("unroll") for (int m = 0; m < 4; ++m) _Pragma("unroll") for (int k = 0; k < 2; ++k) dst[m][k] = *(const LAS bf16x8*)(lds + PG8_SA(b, h) + aoff + m * 2048 + k * 1024); } while (0)
; #define PG8_MMA(ai, bj, At, Bt) do { __builtin_amdgcn_s_setprio(1); _Pragma("unroll") for (int m = 0; m < 4; ++m) _Pragma("unroll") for (int n = 0; n < 2; ++n) _Pragma("unroll") for (int k = 0; k < 2; ++k) \
;         acc[ai][bj][m][n] = __builtin_amdgcn_mfma_f32_16x16x32_bf16(Bt[n][k], At[m][k], acc[ai][bj][m][n], 0, 0, 0); __builtin_amdgcn_s_setprio(0); } while (0)
; #define PG8_WAIT_V(n) asm volatile("s_waitcnt vmcnt(" #n ")" ::: "memory")
; #define PG8_WAIT_L(n) asm volatile("s_waitcnt lgkmcnt(" #n ")" ::: "memory")
; #define PG8_BAR __builtin_amdgcn_s_barrier()
; #define PG8_SCHED __builtin_amdgcn_sched_barrier(0)
; template <class Epi>
; __device__ __forceinline__ void gemm_phase(LAS unsigned char* lds, const Gemm g, const Epi& E) {
;     ...
;             PG8_WAIT_V(8); PG8_WAIT_L(0); PG8_BAR; PG8_MMA(0, 0, At, B0); PG8_MMA(0, 1, At, B1); PG8_BAR; PG8_SCHED;
;             PG8_LDA(At, 1, 1); PG8_STAGE(PG8_SB(1, 0), b3, voffB); PG8_STAGE(PG8_SB(1, 1), b3 + hstepB, voffB); PG8_STAGE(PG8_SA(1, 0), a3, voffA);
;             PG8_WAIT_V(8); PG8_WAIT_L(0); PG8_BAR; PG8_MMA(1, 0, At, B0); PG8_MMA(1, 1, At, B1); PG8_BAR; PG8_SCHED;
;         }
	s_waitcnt lgkmcnt(0)
	v_mfma_f32_16x16x32_bf16 v[126:129], v[140:143], v[182:185], v[126:129]
	v_mfma_f32_16x16x32_bf16 v[122:125], v[158:161], v[182:185], v[122:125]
	v_mfma_f32_16x16x32_bf16 v[110:113], v[140:143], v[190:193], v[110:113]
	v_mfma_f32_16x16x32_bf16 v[106:109], v[158:161], v[190:193], v[106:109]
	v_mfma_f32_16x16x32_bf16 v[94:97], v[140:143], v[198:201], v[94:97]
	v_mfma_f32_16x16x32_bf16 v[90:93], v[158:161], v[198:201], v[90:93]
	v_mfma_f32_16x16x32_bf16 v[78:81], v[140:143], v[224:227], v[78:81]
	v_mfma_f32_16x16x32_bf16 v[74:77], v[158:161], v[224:227], v[74:77]
	v_mfma_f32_16x16x32_bf16 v[126:129], v[154:157], v[186:189], v[126:129]
	v_mfma_f32_16x16x32_bf16 v[122:125], v[162:165], v[186:189], v[122:125]
	v_mfma_f32_16x16x32_bf16 v[110:113], v[154:157], v[194:197], v[110:113]
	v_mfma_f32_16x16x32_bf16 v[106:109], v[162:165], v[194:197], v[106:109]
	v_mfma_f32_16x16x32_bf16 v[94:97], v[154:157], v[202:205], v[94:97]
	v_mfma_f32_16x16x32_bf16 v[90:93], v[162:165], v[202:205], v[90:93]
	v_mfma_f32_16x16x32_bf16 v[78:81], v[154:157], v[228:231], v[78:81]
	v_mfma_f32_16x16x32_bf16 v[74:77], v[162:165], v[228:231], v[74:77]
	v_mfma_f32_16x16x32_bf16 v[118:121], v[166:169], v[182:185], v[118:121]
	v_mfma_f32_16x16x32_bf16 v[114:117], v[174:177], v[182:185], v[114:117]
	v_mfma_f32_16x16x32_bf16 v[102:105], v[166:169], v[190:193], v[102:105]
	v_mfma_f32_16x16x32_bf16 v[98:101], v[174:177], v[190:193], v[98:101]
	v_mfma_f32_16x16x32_bf16 v[86:89], v[166:169], v[198:201], v[86:89]
	v_mfma_f32_16x16x32_bf16 v[82:85], v[174:177], v[198:201], v[82:85]
	v_mfma_f32_16x16x32_bf16 v[70:73], v[166:169], v[224:227], v[70:73]
	v_mfma_f32_16x16x32_bf16 v[66:69], v[174:177], v[224:227], v[66:69]
	v_mfma_f32_16x16x32_bf16 v[118:121], v[170:173], v[186:189], v[118:121]
	v_mfma_f32_16x16x32_bf16 v[114:117], v[178:181], v[186:189], v[114:117]
	v_mfma_f32_16x16x32_bf16 v[102:105], v[170:173], v[194:197], v[102:105]
	v_mfma_f32_16x16x32_bf16 v[98:101], v[178:181], v[194:197], v[98:101]
	v_mfma_f32_16x16x32_bf16 v[86:89], v[170:173], v[202:205], v[86:89]
	v_mfma_f32_16x16x32_bf16 v[82:85], v[178:181], v[202:205], v[82:85]
	v_mfma_f32_16x16x32_bf16 v[70:73], v[170:173], v[228:231], v[70:73]
	v_mfma_f32_16x16x32_bf16 v[66:69], v[178:181], v[228:231], v[66:69]
	s_barrier
	s_add_i32 s62, s71, s6
	v_lshl_add_u64 v[144:145], v[144:145], 0, s[28:29]
	s_mov_b32 m0, s62
	ds_read_b128 v[182:185], v151 offset:49152
	ds_read_b128 v[186:189], v151 offset:50176
	ds_read_b128 v[190:193], v151 offset:51200
	ds_read_b128 v[194:197], v151 offset:52224
	ds_read_b128 v[198:201], v151 offset:53248
	ds_read_b128 v[202:205], v151 offset:54272
	ds_read_b128 v[224:227], v151 offset:55296
	ds_read_b128 v[228:231], v151 offset:56320
	global_load_lds_dwordx4 v[144:145], off
	v_lshl_add_u64 v[144:145], v[206:207], 0, s[28:29]
	s_add_i32 m0, s62, 0x2000
	s_add_i32 s62, s72, s6
	global_load_lds_dwordx4 v[144:145], off
	v_lshl_add_u64 v[144:145], v[220:221], 0, s[28:29]
	s_mov_b32 m0, s62
	s_nop 0
	global_load_lds_dwordx4 v[144:145], off
	v_lshl_add_u64 v[144:145], v[222:223], 0, s[28:29]
	s_add_i32 m0, s62, 0x2000
	s_nop 0
	global_load_lds_dwordx4 v[144:145], off
	v_lshl_add_u64 v[144:145], v[232:233], 0, s[28:29]
	s_mov_b32 m0, s19
	s_nop 0
	global_load_lds_dwordx4 v[144:145], off
	v_lshl_add_u64 v[144:145], v[242:243], 0, s[28:29]
	s_mov_b32 m0, s24
	s_nop 0
	global_load_lds_dwordx4 v[144:145], off
	s_waitcnt vmcnt(8)
	s_waitcnt lgkmcnt(0)
	s_barrier
	s_waitcnt lgkmcnt(0)
	v_mfma_f32_16x16x32_bf16 v[62:65], v[140:143], v[182:185], v[62:65]
	v_mfma_f32_16x16x32_bf16 v[58:61], v[158:161], v[182:185], v[58:61]
	v_mfma_f32_16x16x32_bf16 v[46:49], v[140:143], v[190:193], v[46:49]
	v_mfma_f32_16x16x32_bf16 v[42:45], v[158:161], v[190:193], v[42:45]
	v_mfma_f32_16x16x32_bf16 v[30:33], v[140:143], v[198:201], v[30:33]
	v_mfma_f32_16x16x32_bf16 v[26:29], v[158:161], v[198:201], v[26:29]
	v_mfma_f32_16x16x32_bf16 v[14:17], v[140:143], v[224:227], v[14:17]
	v_mfma_f32_16x16x32_bf16 v[10:13], v[158:161], v[224:227], v[10:13]
	v_mfma_f32_16x16x32_bf16 v[62:65], v[154:157], v[186:189], v[62:65]
	v_mfma_f32_16x16x32_bf16 v[58:61], v[162:165], v[186:189], v[58:61]
	v_mfma_f32_16x16x32_bf16 v[46:49], v[154:157], v[194:197], v[46:49]
	v_mfma_f32_16x16x32_bf16 v[42:45], v[162:165], v[194:197], v[42:45]
	v_mfma_f32_16x16x32_bf16 v[30:33], v[154:157], v[202:205], v[30:33]
	v_mfma_f32_16x16x32_bf16 v[26:29], v[162:165], v[202:205], v[26:29]
	v_mfma_f32_16x16x32_bf16 v[14:17], v[154:157], v[228:231], v[14:17]
	v_mfma_f32_16x16x32_bf16 v[10:13], v[162:165], v[228:231], v[10:13]
	v_mfma_f32_16x16x32_bf16 v[54:57], v[166:169], v[182:185], v[54:57]
	v_mfma_f32_16x16x32_bf16 v[50:53], v[174:177], v[182:185], v[50:53]
	v_mfma_f32_16x16x32_bf16 v[38:41], v[166:169], v[190:193], v[38:41]
	v_mfma_f32_16x16x32_bf16 v[34:37], v[174:177], v[190:193], v[34:37]
	v_mfma_f32_16x16x32_bf16 v[22:25], v[166:169], v[198:201], v[22:25]
	v_mfma_f32_16x16x32_bf16 v[18:21], v[174:177], v[198:201], v[18:21]
	v_mfma_f32_16x16x32_bf16 v[6:9], v[166:169], v[224:227], v[6:9]
	v_mfma_f32_16x16x32_bf16 v[2:5], v[174:177], v[224:227], v[2:5]
	v_mfma_f32_16x16x32_bf16 v[54:57], v[170:173], v[186:189], v[54:57]
	v_mfma_f32_16x16x32_bf16 v[50:53], v[178:181], v[186:189], v[50:53]
	v_mfma_f32_16x16x32_bf16 v[38:41], v[170:173], v[194:197], v[38:41]
	v_mfma_f32_16x16x32_bf16 v[34:37], v[178:181], v[194:197], v[34:37]
	v_mfma_f32_16x16x32_bf16 v[22:25], v[170:173], v[202:205], v[22:25]
	v_mfma_f32_16x16x32_bf16 v[18:21], v[178:181], v[202:205], v[18:21]
	v_mfma_f32_16x16x32_bf16 v[6:9], v[170:173], v[228:231], v[6:9]
	v_mfma_f32_16x16x32_bf16 v[2:5], v[178:181], v[228:231], v[2:5]
	s_barrier
	s_add_u32 s58, s58, 0x100
	s_addc_u32 s59, s59, 0
	s_add_u32 s20, s20, 0x100
	s_addc_u32 s21, s21, 0
	s_cmp_ge_i32 s70, s25
	s_mov_b32 s62, s70
	s_cbranch_scc0 .LBB0_936
	s_setprio 0
